# static s_setprio 1 for the leading wave half before each GEMM K-loop, per-phase setprio flips removed (on top of up-GEMM row-scale prefetch)
# speedup vs baseline: 1.0067x; 1.0067x over previous
; #define PG8_STAGE(bufoff, gbase, voff) do { _Pragma("unroll") for (int _i = 0; _i < 2; ++_i) \
;         __builtin_amdgcn_global_load_lds((const unsigned*)((const char*)(gbase) + (voff)[_i]), (PG8_LAS unsigned*)(lds + (bufoff) + ldsw + _i * 8192), 16, 0, 0); } while (0)
; #define PG8_LDA(dst, b, h) do { _Pragma("unroll") for (int m = 0; m < 4; ++m) _Pragma("unroll") for (int k = 0; k < 2; ++k) dst[m][k] = *(const PG8_LAS bf16x8*)(lds + PG8_SA(b, h) + aoff + m * 2048 + k * 1024); } while (0)
; #define PG8_LDB(dst, b, h) do { _Pragma("unroll") for (int n = 0; n < 2; ++n) _Pragma("unroll") for (int k = 0; k < 2; ++k) dst[n][k] = *(const PG8_LAS bf16x8*)(lds + PG8_SB(b, h) + boff + n * 2048 + k * 1024); } while (0)
; #define PG8_WAIT_V(n) asm volatile("s_waitcnt vmcnt(" #n ")" ::: "memory")
; #define PG8_WAIT_L(n) asm volatile("s_waitcnt lgkmcnt(" #n ")" ::: "memory")
; #define PG8_BAR __builtin_amdgcn_s_barrier()
; #define PG8_SCHED __builtin_amdgcn_sched_barrier(0)
; template <class Epi, class Sched, bool ALIGN_EPI = false, bool SP2 = false>
; __device__ __forceinline__ void gemm_phase(PG8_LAS unsigned char* lds, const Gemm g, const Sched& S, const Epi& E, int tid_in) {
;     ...
;         const char* nA = has_next ? (const char*)g.A + (size_t)nxt.pm * tstep : cA; const char* nB = has_next ? (const char*)g.Bt + (size_t)nxt.pn * tstep : cB;
;         for (int t = 0; t < nt; t += 2) {
;             const bool last = (t == nt - 2);
;             const char* a1 = cA + (size_t)(t + 1) * kstep;
;             const char* a2 = last ? nA : cA + (size_t)(t + 2) * kstep; const char* b2 = last ? nB : cB + (size_t)(t + 2) * kstep;
;             const char* a3 = a2 + kstep; const char* b3 = b2 + kstep;
;             if (last && has_next) S.a_ready(nxt);
;             if constexpr (SP2) {
;             PG8_LDB(B0, 0, 0); PG8_LDB(B1, 0, 1); PG8_SCHED; PG8_LDA(At, 0, 0); PG8_STAGE(PG8_SA(1, 1), a1 + hstep, voffA);
;             PG8_WAIT_V(8); PG8_WAIT_L(0); PG8_BAR; PG8_MMA(0, 0, At, B0); PG8_MMA(0, 1, At, B1); PG8_BAR; PG8_SCHED;
;     ...
;         for (int a = 0; a < 2; ++a)
; #pragma unroll
;             for (int b = 0; b < 2; ++b)
; #pragma unroll
;                 for (int m = 0; m < 4; ++m)
; #pragma unroll
;                     for (int n = 0; n < 2; ++n) acc[a][b][m][n] = (f32x4){0.f, 0.f, 0.f, 0.f};
.LBB0_185:
	s_ashr_i32 s19, s18, 31
	s_lshl_b64 s[20:21], s[18:19], 19
	s_add_u32 s20, s36, s20
	s_addc_u32 s21, s37, s21
	s_and_b64 s[22:23], s[6:7], exec
	s_cselect_b32 s19, s21, s27
	s_cselect_b32 s46, s20, s26
	s_ashr_i32 s17, s16, 31
	s_lshl_b64 s[22:23], s[16:17], 19
	s_add_u32 s22, s41, s22
	s_addc_u32 s23, s44, s23
	s_and_b64 s[30:31], s[6:7], exec
	s_cselect_b32 s17, s23, s29
	s_cselect_b32 s82, s22, s28
	s_add_u32 s26, s26, 0x40080
	s_addc_u32 s27, s27, 0
	s_add_u32 s83, s28, 0x100
	v_mov_b32_e32 v2, 0
	s_addc_u32 s84, s29, 0
	s_mov_b32 s85, -2
	v_mov_b32_e32 v3, v2
	v_mov_b32_e32 v4, v2
	v_mov_b32_e32 v5, v2
	v_mov_b32_e32 v6, v2
	v_mov_b32_e32 v7, v2
	v_mov_b32_e32 v8, v2
	v_mov_b32_e32 v9, v2
	v_mov_b32_e32 v22, v2
	v_mov_b32_e32 v23, v2
	v_mov_b32_e32 v24, v2
	v_mov_b32_e32 v25, v2
	v_mov_b32_e32 v30, v2
	v_mov_b32_e32 v31, v2
	v_mov_b32_e32 v32, v2
	v_mov_b32_e32 v33, v2
	v_mov_b32_e32 v10, v2
	v_mov_b32_e32 v11, v2
	v_mov_b32_e32 v12, v2
	v_mov_b32_e32 v13, v2
	v_mov_b32_e32 v14, v2
	v_mov_b32_e32 v15, v2
	v_mov_b32_e32 v16, v2
	v_mov_b32_e32 v17, v2
	v_mov_b32_e32 v18, v2
	v_mov_b32_e32 v19, v2
	v_mov_b32_e32 v20, v2
	v_mov_b32_e32 v21, v2
	v_mov_b32_e32 v26, v2
	v_mov_b32_e32 v27, v2
	v_mov_b32_e32 v28, v2
	v_mov_b32_e32 v29, v2
	v_mov_b32_e32 v34, v2
	v_mov_b32_e32 v35, v2
	v_mov_b32_e32 v36, v2
	v_mov_b32_e32 v37, v2
	v_mov_b32_e32 v38, v2
	v_mov_b32_e32 v39, v2
	v_mov_b32_e32 v40, v2
	v_mov_b32_e32 v41, v2
	v_mov_b32_e32 v42, v2
	v_mov_b32_e32 v43, v2
	v_mov_b32_e32 v44, v2
	v_mov_b32_e32 v45, v2
	v_mov_b32_e32 v46, v2
	v_mov_b32_e32 v47, v2
	v_mov_b32_e32 v48, v2
	v_mov_b32_e32 v49, v2
	v_mov_b32_e32 v50, v2
	v_mov_b32_e32 v51, v2
	v_mov_b32_e32 v52, v2
	v_mov_b32_e32 v53, v2
	v_mov_b32_e32 v54, v2
	v_mov_b32_e32 v55, v2
	v_mov_b32_e32 v56, v2
	v_mov_b32_e32 v57, v2
	v_mov_b32_e32 v58, v2
	v_mov_b32_e32 v59, v2
	v_mov_b32_e32 v60, v2
	v_mov_b32_e32 v61, v2
	v_mov_b32_e32 v62, v2
	v_mov_b32_e32 v63, v2
	v_mov_b32_e32 v64, v2
	v_mov_b32_e32 v65, v2
	v_mov_b32_e32 v66, v2
	v_mov_b32_e32 v67, v2
	v_mov_b32_e32 v68, v2
	v_mov_b32_e32 v69, v2
	v_mov_b32_e32 v70, v2
	v_mov_b32_e32 v71, v2
	v_mov_b32_e32 v72, v2
	v_mov_b32_e32 v73, v2
	v_mov_b32_e32 v86, v2
	v_mov_b32_e32 v87, v2
	v_mov_b32_e32 v88, v2
	v_mov_b32_e32 v89, v2
	v_mov_b32_e32 v94, v2
	v_mov_b32_e32 v95, v2
	v_mov_b32_e32 v96, v2
	v_mov_b32_e32 v97, v2
	v_mov_b32_e32 v74, v2
	v_mov_b32_e32 v75, v2
	v_mov_b32_e32 v76, v2
	v_mov_b32_e32 v77, v2
	v_mov_b32_e32 v78, v2
	v_mov_b32_e32 v79, v2
	v_mov_b32_e32 v80, v2
	v_mov_b32_e32 v81, v2
	v_mov_b32_e32 v82, v2
	v_mov_b32_e32 v83, v2
	v_mov_b32_e32 v84, v2
	v_mov_b32_e32 v85, v2
	v_mov_b32_e32 v90, v2
	v_mov_b32_e32 v91, v2
	v_mov_b32_e32 v92, v2
	v_mov_b32_e32 v93, v2
	v_mov_b32_e32 v98, v2
	v_mov_b32_e32 v99, v2
	v_mov_b32_e32 v100, v2
	v_mov_b32_e32 v101, v2
	v_mov_b32_e32 v102, v2
	v_mov_b32_e32 v103, v2
	v_mov_b32_e32 v104, v2
	v_mov_b32_e32 v105, v2
	v_mov_b32_e32 v106, v2
	v_mov_b32_e32 v107, v2
	v_mov_b32_e32 v108, v2
	v_mov_b32_e32 v109, v2
	v_mov_b32_e32 v110, v2
	v_mov_b32_e32 v111, v2
	v_mov_b32_e32 v112, v2
	v_mov_b32_e32 v113, v2
	v_mov_b32_e32 v114, v2
	v_mov_b32_e32 v115, v2
	v_mov_b32_e32 v116, v2
	v_mov_b32_e32 v117, v2
	v_mov_b32_e32 v118, v2
	v_mov_b32_e32 v119, v2
	v_mov_b32_e32 v120, v2
	v_mov_b32_e32 v121, v2
	v_mov_b32_e32 v122, v2
	v_mov_b32_e32 v123, v2
	v_mov_b32_e32 v124, v2
	v_mov_b32_e32 v125, v2
	v_mov_b32_e32 v126, v2
	v_mov_b32_e32 v127, v2
	v_mov_b32_e32 v128, v2
	v_mov_b32_e32 v129, v2
	s_and_b64 s[98:99], exec, s[14:15]
	s_cbranch_scc0 .Lprio_skip_186
	s_setprio 1
.Lprio_skip_186:
.LBB0_186:
	s_add_u32 s28, s26, 0xfffc0080
	s_addc_u32 s29, s27, -1
	s_add_i32 s62, 0, 0x10000
	s_cmp_eq_u32 s85, 12
	s_cselect_b32 s31, s19, s29
	s_cselect_b32 s30, s46, s28
	v_add_u32_e32 v140, s62, v157
	s_cselect_b32 s29, s17, s84
	s_cselect_b32 s28, s82, s83
	s_add_i32 s86, 0, 0x14000
	ds_read_b128 v[142:145], v140
	ds_read_b128 v[146:149], v140 offset:1024
	ds_read_b128 v[150:153], v140 offset:2048
	ds_read_b128 v[160:163], v140 offset:3072
	v_add_u32_e32 v140, s86, v157
	ds_read_b128 v[164:167], v140
	ds_read_b128 v[168:171], v140 offset:1024
	ds_read_b128 v[172:175], v140 offset:2048
	ds_read_b128 v[176:179], v140 offset:3072
	v_lshl_add_u64 v[154:155], s[26:27], 0, v[136:137]
	s_add_i32 m0, s49, 0xc000
	ds_read_b128 v[180:183], v159
	ds_read_b128 v[184:187], v159 offset:1024
	ds_read_b128 v[196:199], v159 offset:2048
	ds_read_b128 v[228:231], v159 offset:3072
	ds_read_b128 v[232:235], v159 offset:4096
	ds_read_b128 v[236:239], v159 offset:5120
	ds_read_b128 v[240:243], v159 offset:6144
	ds_read_b128 v[244:247], v159 offset:7168
	global_load_lds_dwordx4 v[154:155], off
	v_lshl_add_u64 v[154:155], s[26:27], 0, v[138:139]
	s_add_i32 m0, s49, 0xe000
	s_nop 0
	global_load_lds_dwordx4 v[154:155], off
	s_waitcnt vmcnt(8)
	s_waitcnt lgkmcnt(0)
	s_barrier
; #define PG8_STAGE(bufoff, gbase, voff) do { _Pragma("unroll") for (int _i = 0; _i < 2; ++_i) \
;         __builtin_amdgcn_global_load_lds((const unsigned*)((const char*)(gbase) + (voff)[_i]), (PG8_LAS unsigned*)(lds + (bufoff) + ldsw + _i * 8192), 16, 0, 0); } while (0)
; #define PG8_LDA(dst, b, h) do { _Pragma("unroll") for (int m = 0; m < 4; ++m) _Pragma("unroll") for (int k = 0; k < 2; ++k) dst[m][k] = *(const PG8_LAS bf16x8*)(lds + PG8_SA(b, h) + aoff + m * 2048 + k * 1024); } while (0)
; #define PG8_LDB(dst, b, h) do { _Pragma("unroll") for (int n = 0; n < 2; ++n) _Pragma("unroll") for (int k = 0; k < 2; ++k) dst[n][k] = *(const PG8_LAS bf16x8*)(lds + PG8_SB(b, h) + boff + n * 2048 + k * 1024); } while (0)
; #define PG8_MMA(ai, bj, At, Bt) do { __builtin_amdgcn_s_setprio(1); _Pragma("unroll") for (int m = 0; m < 4; ++m) _Pragma("unroll") for (int n = 0; n < 2; ++n) _Pragma("unroll") for (int k = 0; k < 2; ++k) \
;         acc[ai][bj][m][n] = __builtin_amdgcn_mfma_f32_16x16x32_bf16(Bt[n][k], At[m][k], acc[ai][bj][m][n], 0, 0, 0); __builtin_amdgcn_s_setprio(0); } while (0)
; #define PG8_WAIT_V(n) asm volatile("s_waitcnt vmcnt(" #n ")" ::: "memory")
; #define PG8_WAIT_L(n) asm volatile("s_waitcnt lgkmcnt(" #n ")" ::: "memory")
; #define PG8_BAR __builtin_amdgcn_s_barrier()
; #define PG8_SCHED __builtin_amdgcn_sched_barrier(0)
; template <class Epi, class Sched, bool ALIGN_EPI = false, bool SP2 = false>
; __device__ __forceinline__ void gemm_phase(PG8_LAS unsigned char* lds, const Gemm g, const Sched& S, const Epi& E, int tid_in) {
;     ...
;             PG8_LDB(B0, 0, 0); PG8_LDB(B1, 0, 1); PG8_SCHED; PG8_LDA(At, 0, 0); PG8_STAGE(PG8_SA(1, 1), a1 + hstep, voffA);
;             PG8_WAIT_V(8); PG8_WAIT_L(0); PG8_BAR; PG8_MMA(0, 0, At, B0); PG8_MMA(0, 1, At, B1); PG8_BAR; PG8_SCHED;
;             PG8_LDA(At, 0, 1); PG8_STAGE(PG8_SB(0, 0), b2, voffB); PG8_STAGE(PG8_SB(0, 1), b2 + hstep, voffB); PG8_STAGE(PG8_SA(0, 0), a2, voffA);
;             PG8_WAIT_V(8); PG8_WAIT_L(0); PG8_BAR; PG8_MMA(1, 0, At, B0); PG8_MMA(1, 1, At, B1); PG8_BAR; PG8_SCHED;
	s_waitcnt lgkmcnt(0)
	v_mfma_f32_16x16x32_bf16 v[126:129], v[142:145], v[180:183], v[126:129]
	v_mfma_f32_16x16x32_bf16 v[122:125], v[150:153], v[180:183], v[122:125]
	v_mfma_f32_16x16x32_bf16 v[118:121], v[142:145], v[196:199], v[118:121]
	v_mfma_f32_16x16x32_bf16 v[114:117], v[150:153], v[196:199], v[114:117]
	v_mfma_f32_16x16x32_bf16 v[110:113], v[142:145], v[232:235], v[110:113]
	v_mfma_f32_16x16x32_bf16 v[106:109], v[150:153], v[232:235], v[106:109]
	v_mfma_f32_16x16x32_bf16 v[102:105], v[142:145], v[240:243], v[102:105]
	v_mfma_f32_16x16x32_bf16 v[98:101], v[150:153], v[240:243], v[98:101]
	v_mfma_f32_16x16x32_bf16 v[126:129], v[146:149], v[184:187], v[126:129]
	v_mfma_f32_16x16x32_bf16 v[122:125], v[160:163], v[184:187], v[122:125]
	v_mfma_f32_16x16x32_bf16 v[118:121], v[146:149], v[228:231], v[118:121]
	v_mfma_f32_16x16x32_bf16 v[114:117], v[160:163], v[228:231], v[114:117]
	v_mfma_f32_16x16x32_bf16 v[110:113], v[146:149], v[236:239], v[110:113]
	v_mfma_f32_16x16x32_bf16 v[106:109], v[160:163], v[236:239], v[106:109]
	v_mfma_f32_16x16x32_bf16 v[102:105], v[146:149], v[244:247], v[102:105]
	v_mfma_f32_16x16x32_bf16 v[98:101], v[160:163], v[244:247], v[98:101]
	v_mfma_f32_16x16x32_bf16 v[90:93], v[164:167], v[180:183], v[90:93]
	v_mfma_f32_16x16x32_bf16 v[82:85], v[172:175], v[180:183], v[82:85]
	v_mfma_f32_16x16x32_bf16 v[78:81], v[164:167], v[196:199], v[78:81]
	v_mfma_f32_16x16x32_bf16 v[74:77], v[172:175], v[196:199], v[74:77]
	v_mfma_f32_16x16x32_bf16 v[94:97], v[164:167], v[232:235], v[94:97]
	v_mfma_f32_16x16x32_bf16 v[86:89], v[172:175], v[232:235], v[86:89]
	v_mfma_f32_16x16x32_bf16 v[70:73], v[164:167], v[240:243], v[70:73]
	v_mfma_f32_16x16x32_bf16 v[66:69], v[172:175], v[240:243], v[66:69]
	v_mfma_f32_16x16x32_bf16 v[90:93], v[168:171], v[184:187], v[90:93]
	v_mfma_f32_16x16x32_bf16 v[82:85], v[176:179], v[184:187], v[82:85]
	v_mfma_f32_16x16x32_bf16 v[78:81], v[168:171], v[228:231], v[78:81]
	v_mfma_f32_16x16x32_bf16 v[74:77], v[176:179], v[228:231], v[74:77]
	v_mfma_f32_16x16x32_bf16 v[94:97], v[168:171], v[236:239], v[94:97]
	v_mfma_f32_16x16x32_bf16 v[86:89], v[176:179], v[236:239], v[86:89]
	v_mfma_f32_16x16x32_bf16 v[70:73], v[168:171], v[244:247], v[70:73]
	v_mfma_f32_16x16x32_bf16 v[66:69], v[176:179], v[244:247], v[66:69]
	s_barrier
	s_add_i32 s62, s62, s47
	v_lshl_add_u64 v[154:155], s[28:29], 0, v[0:1]
	s_mov_b32 m0, s62
	ds_read_b128 v[180:183], v159 offset:16384
	ds_read_b128 v[184:187], v159 offset:17408
	ds_read_b128 v[196:199], v159 offset:18432
	ds_read_b128 v[228:231], v159 offset:19456
	ds_read_b128 v[232:235], v159 offset:20480
	ds_read_b128 v[236:239], v159 offset:21504
	ds_read_b128 v[240:243], v159 offset:22528
	ds_read_b128 v[244:247], v159 offset:23552
	global_load_lds_dwordx4 v[154:155], off
	s_add_i32 m0, s62, 0x2000
	s_add_u32 s62, s28, 0x40000
	v_lshl_add_u64 v[248:249], s[28:29], 0, v[130:131]
	s_addc_u32 s63, s29, 0
	s_add_i32 s86, s86, s47
	global_load_lds_dwordx4 v[248:249], off
	v_lshl_add_u64 v[250:251], s[62:63], 0, v[0:1]
	s_mov_b32 m0, s86
	v_lshl_add_u64 v[252:253], s[30:31], 0, v[132:133]
	global_load_lds_dwordx4 v[250:251], off
	v_lshl_add_u64 v[250:251], s[62:63], 0, v[130:131]
	s_add_i32 m0, s86, 0x2000
	s_nop 0
	global_load_lds_dwordx4 v[250:251], off
	v_lshl_add_u64 v[250:251], s[30:31], 0, v[134:135]
	s_mov_b32 m0, s49
	s_nop 0
	global_load_lds_dwordx4 v[250:251], off
	s_mov_b32 m0, s70
	s_nop 0
	global_load_lds_dwordx4 v[252:253], off
	s_waitcnt vmcnt(8)
	s_waitcnt lgkmcnt(0)
	s_barrier
	s_waitcnt lgkmcnt(0)
	v_mfma_f32_16x16x32_bf16 v[62:65], v[142:145], v[180:183], v[62:65]
	v_mfma_f32_16x16x32_bf16 v[58:61], v[150:153], v[180:183], v[58:61]
	v_mfma_f32_16x16x32_bf16 v[54:57], v[142:145], v[196:199], v[54:57]
	v_mfma_f32_16x16x32_bf16 v[50:53], v[150:153], v[196:199], v[50:53]
	v_mfma_f32_16x16x32_bf16 v[46:49], v[142:145], v[232:235], v[46:49]
	v_mfma_f32_16x16x32_bf16 v[42:45], v[150:153], v[232:235], v[42:45]
	v_mfma_f32_16x16x32_bf16 v[38:41], v[142:145], v[240:243], v[38:41]
	v_mfma_f32_16x16x32_bf16 v[34:37], v[150:153], v[240:243], v[34:37]
	v_mfma_f32_16x16x32_bf16 v[62:65], v[146:149], v[184:187], v[62:65]
	v_mfma_f32_16x16x32_bf16 v[58:61], v[160:163], v[184:187], v[58:61]
	v_mfma_f32_16x16x32_bf16 v[54:57], v[146:149], v[228:231], v[54:57]
	v_mfma_f32_16x16x32_bf16 v[50:53], v[160:163], v[228:231], v[50:53]
	v_mfma_f32_16x16x32_bf16 v[46:49], v[146:149], v[236:239], v[46:49]
	v_mfma_f32_16x16x32_bf16 v[42:45], v[160:163], v[236:239], v[42:45]
	v_mfma_f32_16x16x32_bf16 v[38:41], v[146:149], v[244:247], v[38:41]
	v_mfma_f32_16x16x32_bf16 v[34:37], v[160:163], v[244:247], v[34:37]
	v_mfma_f32_16x16x32_bf16 v[26:29], v[164:167], v[180:183], v[26:29]
	v_mfma_f32_16x16x32_bf16 v[18:21], v[172:175], v[180:183], v[18:21]
	v_mfma_f32_16x16x32_bf16 v[14:17], v[164:167], v[196:199], v[14:17]
	v_mfma_f32_16x16x32_bf16 v[10:13], v[172:175], v[196:199], v[10:13]
	v_mfma_f32_16x16x32_bf16 v[30:33], v[164:167], v[232:235], v[30:33]
	v_mfma_f32_16x16x32_bf16 v[22:25], v[172:175], v[232:235], v[22:25]
	v_mfma_f32_16x16x32_bf16 v[6:9], v[164:167], v[240:243], v[6:9]
	v_mfma_f32_16x16x32_bf16 v[2:5], v[172:175], v[240:243], v[2:5]
	v_mfma_f32_16x16x32_bf16 v[26:29], v[168:171], v[184:187], v[26:29]
	v_mfma_f32_16x16x32_bf16 v[18:21], v[176:179], v[184:187], v[18:21]
	v_mfma_f32_16x16x32_bf16 v[14:17], v[168:171], v[228:231], v[14:17]
	v_mfma_f32_16x16x32_bf16 v[10:13], v[176:179], v[228:231], v[10:13]
	v_mfma_f32_16x16x32_bf16 v[30:33], v[168:171], v[236:239], v[30:33]
	v_mfma_f32_16x16x32_bf16 v[22:25], v[176:179], v[236:239], v[22:25]
	v_mfma_f32_16x16x32_bf16 v[6:9], v[168:171], v[244:247], v[6:9]
	v_mfma_f32_16x16x32_bf16 v[2:5], v[176:179], v[244:247], v[2:5]
	s_barrier
; #define PG8_STAGE(bufoff, gbase, voff) do { _Pragma("unroll") for (int _i = 0; _i < 2; ++_i) \
;         __builtin_amdgcn_global_load_lds((const unsigned*)((const char*)(gbase) + (voff)[_i]), (PG8_LAS unsigned*)(lds + (bufoff) + ldsw + _i * 8192), 16, 0, 0); } while (0)
; #define PG8_LDA(dst, b, h) do { _Pragma("unroll") for (int m = 0; m < 4; ++m) _Pragma("unroll") for (int k = 0; k < 2; ++k) dst[m][k] = *(const PG8_LAS bf16x8*)(lds + PG8_SA(b, h) + aoff + m * 2048 + k * 1024); } while (0)
; #define PG8_LDB(dst, b, h) do { _Pragma("unroll") for (int n = 0; n < 2; ++n) _Pragma("unroll") for (int k = 0; k < 2; ++k) dst[n][k] = *(const PG8_LAS bf16x8*)(lds + PG8_SB(b, h) + boff + n * 2048 + k * 1024); } while (0)
; #define PG8_MMA(ai, bj, At, Bt) do { __builtin_amdgcn_s_setprio(1); _Pragma("unroll") for (int m = 0; m < 4; ++m) _Pragma("unroll") for (int n = 0; n < 2; ++n) _Pragma("unroll") for (int k = 0; k < 2; ++k) \
;         acc[ai][bj][m][n] = __builtin_amdgcn_mfma_f32_16x16x32_bf16(Bt[n][k], At[m][k], acc[ai][bj][m][n], 0, 0, 0); __builtin_amdgcn_s_setprio(0); } while (0)
; #define PG8_WAIT_V(n) asm volatile("s_waitcnt vmcnt(" #n ")" ::: "memory")
; #define PG8_WAIT_L(n) asm volatile("s_waitcnt lgkmcnt(" #n ")" ::: "memory")
; #define PG8_BAR __builtin_amdgcn_s_barrier()
; #define PG8_SCHED __builtin_amdgcn_sched_barrier(0)
; template <class Epi, class Sched, bool ALIGN_EPI = false, bool SP2 = false>
; __device__ __forceinline__ void gemm_phase(PG8_LAS unsigned char* lds, const Gemm g, const Sched& S, const Epi& E, int tid_in) {
;     ...
;             PG8_LDB(B0, 1, 0); PG8_LDB(B1, 1, 1); PG8_SCHED; PG8_LDA(At, 1, 0); PG8_STAGE(PG8_SA(0, 1), a2 + hstep, voffA);
;             PG8_WAIT_V(8); PG8_WAIT_L(0); PG8_BAR; PG8_MMA(0, 0, At, B0); PG8_MMA(0, 1, At, B1); PG8_BAR; PG8_SCHED;
	s_add_i32 s62, 0, 0x18000
	v_add_u32_e32 v140, s62, v157
	s_add_i32 s63, 0, 0x1c000
	ds_read_b128 v[142:145], v140
	ds_read_b128 v[146:149], v140 offset:1024
	ds_read_b128 v[150:153], v140 offset:2048
	ds_read_b128 v[160:163], v140 offset:3072
	v_add_u32_e32 v140, s63, v157
	ds_read_b128 v[164:167], v140
	ds_read_b128 v[168:171], v140 offset:1024
	ds_read_b128 v[172:175], v140 offset:2048
	ds_read_b128 v[176:179], v140 offset:3072
	s_add_u32 s30, s30, 0x40000
	s_addc_u32 s31, s31, 0
	s_mov_b32 m0, s71
	v_lshl_add_u64 v[218:219], s[30:31], 0, v[134:135]
	ds_read_b128 v[180:183], v159 offset:32768
	ds_read_b128 v[184:187], v159 offset:33792
	ds_read_b128 v[196:199], v159 offset:34816
	ds_read_b128 v[228:231], v159 offset:35840
	ds_read_b128 v[232:235], v159 offset:36864
	ds_read_b128 v[236:239], v159 offset:37888
	ds_read_b128 v[240:243], v159 offset:38912
	ds_read_b128 v[244:247], v159 offset:39936
	global_load_lds_dwordx4 v[218:219], off
	v_lshl_add_u64 v[218:219], s[30:31], 0, v[132:133]
	s_mov_b32 m0, s72
	s_nop 0
	global_load_lds_dwordx4 v[218:219], off
	s_waitcnt vmcnt(8)
	s_waitcnt lgkmcnt(0)
	s_barrier
	s_waitcnt lgkmcnt(0)
	v_mfma_f32_16x16x32_bf16 v[126:129], v[142:145], v[180:183], v[126:129]
	v_mfma_f32_16x16x32_bf16 v[122:125], v[150:153], v[180:183], v[122:125]
	v_mfma_f32_16x16x32_bf16 v[118:121], v[142:145], v[196:199], v[118:121]
	v_mfma_f32_16x16x32_bf16 v[114:117], v[150:153], v[196:199], v[114:117]
	v_mfma_f32_16x16x32_bf16 v[110:113], v[142:145], v[232:235], v[110:113]
	v_mfma_f32_16x16x32_bf16 v[106:109], v[150:153], v[232:235], v[106:109]
	v_mfma_f32_16x16x32_bf16 v[102:105], v[142:145], v[240:243], v[102:105]
	v_mfma_f32_16x16x32_bf16 v[98:101], v[150:153], v[240:243], v[98:101]
	v_mfma_f32_16x16x32_bf16 v[126:129], v[146:149], v[184:187], v[126:129]
	v_mfma_f32_16x16x32_bf16 v[122:125], v[160:163], v[184:187], v[122:125]
	v_mfma_f32_16x16x32_bf16 v[118:121], v[146:149], v[228:231], v[118:121]
	v_mfma_f32_16x16x32_bf16 v[114:117], v[160:163], v[228:231], v[114:117]
	v_mfma_f32_16x16x32_bf16 v[110:113], v[146:149], v[236:239], v[110:113]
	v_mfma_f32_16x16x32_bf16 v[106:109], v[160:163], v[236:239], v[106:109]
	v_mfma_f32_16x16x32_bf16 v[102:105], v[146:149], v[244:247], v[102:105]
	v_mfma_f32_16x16x32_bf16 v[98:101], v[160:163], v[244:247], v[98:101]
	v_mfma_f32_16x16x32_bf16 v[90:93], v[164:167], v[180:183], v[90:93]
	v_mfma_f32_16x16x32_bf16 v[82:85], v[172:175], v[180:183], v[82:85]
	v_mfma_f32_16x16x32_bf16 v[78:81], v[164:167], v[196:199], v[78:81]
	v_mfma_f32_16x16x32_bf16 v[74:77], v[172:175], v[196:199], v[74:77]
	v_mfma_f32_16x16x32_bf16 v[94:97], v[164:167], v[232:235], v[94:97]
	v_mfma_f32_16x16x32_bf16 v[86:89], v[172:175], v[232:235], v[86:89]
	v_mfma_f32_16x16x32_bf16 v[70:73], v[164:167], v[240:243], v[70:73]
	v_mfma_f32_16x16x32_bf16 v[66:69], v[172:175], v[240:243], v[66:69]
	v_mfma_f32_16x16x32_bf16 v[90:93], v[168:171], v[184:187], v[90:93]
	v_mfma_f32_16x16x32_bf16 v[82:85], v[176:179], v[184:187], v[82:85]
	v_mfma_f32_16x16x32_bf16 v[78:81], v[168:171], v[228:231], v[78:81]
	v_mfma_f32_16x16x32_bf16 v[74:77], v[176:179], v[228:231], v[74:77]
	v_mfma_f32_16x16x32_bf16 v[94:97], v[168:171], v[236:239], v[94:97]
	v_mfma_f32_16x16x32_bf16 v[86:89], v[176:179], v[236:239], v[86:89]
	v_mfma_f32_16x16x32_bf16 v[70:73], v[168:171], v[244:247], v[70:73]
	v_mfma_f32_16x16x32_bf16 v[66:69], v[176:179], v[244:247], v[66:69]
	s_barrier
; #define PG8_STAGE(bufoff, gbase, voff) do { _Pragma("unroll") for (int _i = 0; _i < 2; ++_i) \
;         __builtin_amdgcn_global_load_lds((const unsigned*)((const char*)(gbase) + (voff)[_i]), (PG8_LAS unsigned*)(lds + (bufoff) + ldsw + _i * 8192), 16, 0, 0); } while (0)
; #define PG8_LDA(dst, b, h) do { _Pragma("unroll") for (int m = 0; m < 4; ++m) _Pragma("unroll") for (int k = 0; k < 2; ++k) dst[m][k] = *(const PG8_LAS bf16x8*)(lds + PG8_SA(b, h) + aoff + m * 2048 + k * 1024); } while (0)
; #define PG8_BAR __builtin_amdgcn_s_barrier()
; template <class Epi, class Sched, bool ALIGN_EPI = false, bool SP2 = false>
; __device__ __forceinline__ void gemm_phase(PG8_LAS unsigned char* lds, const Gemm g, const Sched& S, const Epi& E, int tid_in) {
;     ...
;             PG8_LDA(At, 1, 1); PG8_STAGE(PG8_SB(1, 0), b3, voffB); PG8_STAGE(PG8_SB(1, 1), b3 + hstep, voffB); PG8_STAGE(PG8_SA(1, 0), a3, voffA);
;             PG8_WAIT_V(8); PG8_WAIT_L(0); PG8_BAR; PG8_MMA(1, 0, At, B0); PG8_MMA(1, 1, At, B1); PG8_BAR; PG8_SCHED;
;             } else {
;             PG8_LDB(B0, 0, 0); PG8_SCHED; PG8_LDA(At, 0, 0); PG8_STAGE(PG8_SA(1, 1), a1 + hstep, voffA);
;             PG8_WAIT_L(8); PG8_BAR; PG8_WAIT_L(0); PG8_MMA(0, 0, At, B0); PG8_BAR; PG8_SCHED;
;             PG8_LDB(B1, 0, 1); PG8_STAGE(PG8_SB(0, 0), b2, voffB);
;             PG8_BAR; PG8_WAIT_L(0); PG8_MMA(0, 1, At, B1); PG8_BAR;
;             PG8_LDA(At, 0, 1); PG8_STAGE(PG8_SA(0, 0), a2, voffA);
;             PG8_BAR; PG8_WAIT_L(0); PG8_MMA(1, 0, At, B0); PG8_BAR; PG8_SCHED;
;             PG8_STAGE(PG8_SB(0, 1), b2 + hstep, voffB);
;             PG8_WAIT_V(6); PG8_BAR; PG8_MMA(1, 1, At, B1); PG8_BAR;
;             PG8_LDB(B0, 1, 0); PG8_SCHED; PG8_LDA(At, 1, 0); PG8_STAGE(PG8_SA(0, 1), a2 + hstep, voffA);
;             PG8_WAIT_L(8); PG8_BAR; PG8_WAIT_L(0); PG8_MMA(0, 0, At, B0); PG8_BAR; PG8_SCHED;
;             PG8_LDB(B1, 1, 1); PG8_STAGE(PG8_SB(1, 0), b3, voffB);
;             PG8_BAR; PG8_WAIT_L(0); PG8_MMA(0, 1, At, B1); PG8_BAR;
;             PG8_LDA(At, 1, 1); PG8_STAGE(PG8_SA(1, 0), a3, voffA);
;             PG8_BAR; PG8_WAIT_L(0); PG8_MMA(1, 0, At, B0); PG8_BAR; PG8_SCHED;
;             PG8_STAGE(PG8_SB(1, 1), b3 + hstep, voffB);
;             PG8_WAIT_V(6); PG8_BAR; PG8_MMA(1, 1, At, B1); PG8_BAR;
;             }
;         }
;         if constexpr (ALIGN_EPI) { if (wr == 0) PG8_BAR; }
	s_add_i32 s30, s62, s47
	v_lshl_add_u64 v[154:155], v[154:155], 0, s[54:55]
	s_mov_b32 m0, s30
	ds_read_b128 v[180:183], v159 offset:49152
	ds_read_b128 v[184:187], v159 offset:50176
	ds_read_b128 v[196:199], v159 offset:51200
	ds_read_b128 v[228:231], v159 offset:52224
	ds_read_b128 v[232:235], v159 offset:53248
	ds_read_b128 v[236:239], v159 offset:54272
	ds_read_b128 v[240:243], v159 offset:55296
	ds_read_b128 v[244:247], v159 offset:56320
	global_load_lds_dwordx4 v[154:155], off
	s_add_i32 m0, s30, 0x2000
	s_add_u32 s28, s28, 0x40080
	v_lshl_add_u64 v[154:155], v[248:249], 0, s[54:55]
	s_addc_u32 s29, s29, 0
	s_add_i32 s30, s63, s47
	global_load_lds_dwordx4 v[154:155], off
	v_lshl_add_u64 v[154:155], s[28:29], 0, v[0:1]
	s_mov_b32 m0, s30
	s_nop 0
	global_load_lds_dwordx4 v[154:155], off
	v_lshl_add_u64 v[154:155], s[28:29], 0, v[130:131]
	s_add_i32 m0, s30, 0x2000
	s_nop 0
	global_load_lds_dwordx4 v[154:155], off
	v_lshl_add_u64 v[154:155], v[250:251], 0, s[54:55]
	s_mov_b32 m0, s75
	s_nop 0
	global_load_lds_dwordx4 v[154:155], off
	v_lshl_add_u64 v[154:155], v[252:253], 0, s[54:55]
	s_mov_b32 m0, s76
	s_nop 0
	global_load_lds_dwordx4 v[154:155], off
	s_waitcnt vmcnt(8)
	s_waitcnt lgkmcnt(0)
	s_barrier
	s_waitcnt lgkmcnt(0)
	v_mfma_f32_16x16x32_bf16 v[62:65], v[142:145], v[180:183], v[62:65]
	v_mfma_f32_16x16x32_bf16 v[58:61], v[150:153], v[180:183], v[58:61]
	v_mfma_f32_16x16x32_bf16 v[54:57], v[142:145], v[196:199], v[54:57]
	v_mfma_f32_16x16x32_bf16 v[50:53], v[150:153], v[196:199], v[50:53]
	v_mfma_f32_16x16x32_bf16 v[46:49], v[142:145], v[232:235], v[46:49]
	v_mfma_f32_16x16x32_bf16 v[42:45], v[150:153], v[232:235], v[42:45]
	v_mfma_f32_16x16x32_bf16 v[38:41], v[142:145], v[240:243], v[38:41]
	v_mfma_f32_16x16x32_bf16 v[34:37], v[150:153], v[240:243], v[34:37]
	v_mfma_f32_16x16x32_bf16 v[62:65], v[146:149], v[184:187], v[62:65]
	v_mfma_f32_16x16x32_bf16 v[58:61], v[160:163], v[184:187], v[58:61]
	v_mfma_f32_16x16x32_bf16 v[54:57], v[146:149], v[228:231], v[54:57]
	v_mfma_f32_16x16x32_bf16 v[50:53], v[160:163], v[228:231], v[50:53]
	v_mfma_f32_16x16x32_bf16 v[46:49], v[146:149], v[236:239], v[46:49]
	v_mfma_f32_16x16x32_bf16 v[42:45], v[160:163], v[236:239], v[42:45]
	v_mfma_f32_16x16x32_bf16 v[38:41], v[146:149], v[244:247], v[38:41]
	v_mfma_f32_16x16x32_bf16 v[34:37], v[160:163], v[244:247], v[34:37]
	v_mfma_f32_16x16x32_bf16 v[26:29], v[164:167], v[180:183], v[26:29]
	v_mfma_f32_16x16x32_bf16 v[18:21], v[172:175], v[180:183], v[18:21]
	v_mfma_f32_16x16x32_bf16 v[14:17], v[164:167], v[196:199], v[14:17]
	v_mfma_f32_16x16x32_bf16 v[10:13], v[172:175], v[196:199], v[10:13]
	v_mfma_f32_16x16x32_bf16 v[30:33], v[164:167], v[232:235], v[30:33]
	v_mfma_f32_16x16x32_bf16 v[22:25], v[172:175], v[232:235], v[22:25]
	v_mfma_f32_16x16x32_bf16 v[6:9], v[164:167], v[240:243], v[6:9]
	v_mfma_f32_16x16x32_bf16 v[2:5], v[172:175], v[240:243], v[2:5]
	v_mfma_f32_16x16x32_bf16 v[26:29], v[168:171], v[184:187], v[26:29]
	v_mfma_f32_16x16x32_bf16 v[18:21], v[176:179], v[184:187], v[18:21]
	v_mfma_f32_16x16x32_bf16 v[14:17], v[168:171], v[228:231], v[14:17]
	v_mfma_f32_16x16x32_bf16 v[10:13], v[176:179], v[228:231], v[10:13]
	v_mfma_f32_16x16x32_bf16 v[30:33], v[168:171], v[236:239], v[30:33]
	v_mfma_f32_16x16x32_bf16 v[22:25], v[176:179], v[236:239], v[22:25]
	v_mfma_f32_16x16x32_bf16 v[6:9], v[168:171], v[244:247], v[6:9]
	v_mfma_f32_16x16x32_bf16 v[2:5], v[176:179], v[244:247], v[2:5]
	s_barrier
	s_add_i32 s85, s85, 2
	s_add_u32 s26, s26, 0x100
	s_addc_u32 s27, s27, 0
	s_add_u32 s83, s83, 0x100
	s_addc_u32 s84, s84, 0
	s_cmp_gt_u32 s85, 13
	s_cbranch_scc0 .LBB0_186
	s_setprio 0
	s_and_b64 vcc, exec, s[14:15]
	s_cbranch_vccz .LBB0_189
	s_barrier

; #define PG8_STAGE(bufoff, gbase, voff) do { _Pragma("unroll") for (int _i = 0; _i < 2; ++_i) \
;         __builtin_amdgcn_global_load_lds((const unsigned*)((const char*)(gbase) + (voff)[_i]), (PG8_LAS unsigned*)(lds + (bufoff) + ldsw + _i * 8192), 16, 0, 0); } while (0)
; #define PG8_LDA(dst, b, h) do { _Pragma("unroll") for (int m = 0; m < 4; ++m) _Pragma("unroll") for (int k = 0; k < 2; ++k) dst[m][k] = *(const PG8_LAS bf16x8*)(lds + PG8_SA(b, h) + aoff + m * 2048 + k * 1024); } while (0)
; #define PG8_LDB(dst, b, h) do { _Pragma("unroll") for (int n = 0; n < 2; ++n) _Pragma("unroll") for (int k = 0; k < 2; ++k) dst[n][k] = *(const PG8_LAS bf16x8*)(lds + PG8_SB(b, h) + boff + n * 2048 + k * 1024); } while (0)
; #define PG8_WAIT_V(n) asm volatile("s_waitcnt vmcnt(" #n ")" ::: "memory")
; #define PG8_WAIT_L(n) asm volatile("s_waitcnt lgkmcnt(" #n ")" ::: "memory")
; #define PG8_BAR __builtin_amdgcn_s_barrier()
; #define PG8_SCHED __builtin_amdgcn_sched_barrier(0)
; template <class Epi, class Sched, bool ALIGN_EPI = false, bool SP2 = false>
; __device__ __forceinline__ void gemm_phase(PG8_LAS unsigned char* lds, const Gemm g, const Sched& S, const Epi& E, int tid_in) {
;     ...
;         const char* nA = has_next ? (const char*)g.A + (size_t)nxt.pm * tstep : cA; const char* nB = has_next ? (const char*)g.Bt + (size_t)nxt.pn * tstep : cB;
;         for (int t = 0; t < nt; t += 2) {
;             const bool last = (t == nt - 2);
;             const char* a1 = cA + (size_t)(t + 1) * kstep;
;             const char* a2 = last ? nA : cA + (size_t)(t + 2) * kstep; const char* b2 = last ? nB : cB + (size_t)(t + 2) * kstep;
;             const char* a3 = a2 + kstep; const char* b3 = b2 + kstep;
;             if (last && has_next) S.a_ready(nxt);
;             if constexpr (SP2) {
;             PG8_LDB(B0, 0, 0); PG8_LDB(B1, 0, 1); PG8_SCHED; PG8_LDA(At, 0, 0); PG8_STAGE(PG8_SA(1, 1), a1 + hstep, voffA);
;             PG8_WAIT_V(8); PG8_WAIT_L(0); PG8_BAR; PG8_MMA(0, 0, At, B0); PG8_MMA(0, 1, At, B1); PG8_BAR; PG8_SCHED;
;     ...
;         for (int a = 0; a < 2; ++a)
; #pragma unroll
;             for (int b = 0; b < 2; ++b)
; #pragma unroll
;                 for (int m = 0; m < 4; ++m)
; #pragma unroll
;                     for (int n = 0; n < 2; ++n) acc[a][b][m][n] = (f32x4){0.f, 0.f, 0.f, 0.f};
.LBB0_537:
	s_ashr_i32 s15, s14, 31
	s_lshl_b64 s[18:19], s[14:15], 19
	s_add_u32 s18, s30, s18
	s_addc_u32 s19, s31, s19
	s_and_b64 s[20:21], s[4:5], exec
	s_cselect_b32 s15, s19, s23
	s_cselect_b32 s71, s18, s22
	s_ashr_i32 s13, s12, 31
	s_lshl_b64 s[20:21], s[12:13], 19
	s_add_u32 s20, s34, s20
	s_addc_u32 s21, s35, s21
	s_and_b64 s[26:27], s[4:5], exec
	s_cselect_b32 s13, s21, s25
	s_cselect_b32 s72, s20, s24
	s_add_u32 s22, s22, 0x40080
	s_addc_u32 s23, s23, 0
	s_add_u32 s73, s24, 0x100
	v_mov_b32_e32 v2, 0
	s_addc_u32 s74, s25, 0
	s_mov_b32 s75, -2
	v_mov_b32_e32 v3, v2
	v_mov_b32_e32 v4, v2
	v_mov_b32_e32 v5, v2
	v_mov_b32_e32 v6, v2
	v_mov_b32_e32 v7, v2
	v_mov_b32_e32 v8, v2
	v_mov_b32_e32 v9, v2
	v_mov_b32_e32 v10, v2
	v_mov_b32_e32 v11, v2
	v_mov_b32_e32 v12, v2
	v_mov_b32_e32 v13, v2
	v_mov_b32_e32 v18, v2
	v_mov_b32_e32 v19, v2
	v_mov_b32_e32 v20, v2
	v_mov_b32_e32 v21, v2
	v_mov_b32_e32 v26, v2
	v_mov_b32_e32 v27, v2
	v_mov_b32_e32 v28, v2
	v_mov_b32_e32 v29, v2
	v_mov_b32_e32 v34, v2
	v_mov_b32_e32 v35, v2
	v_mov_b32_e32 v36, v2
	v_mov_b32_e32 v37, v2
	v_mov_b32_e32 v42, v2
	v_mov_b32_e32 v43, v2
	v_mov_b32_e32 v44, v2
	v_mov_b32_e32 v45, v2
	v_mov_b32_e32 v50, v2
	v_mov_b32_e32 v51, v2
	v_mov_b32_e32 v52, v2
	v_mov_b32_e32 v53, v2
	v_mov_b32_e32 v14, v2
	v_mov_b32_e32 v15, v2
	v_mov_b32_e32 v16, v2
	v_mov_b32_e32 v17, v2
	v_mov_b32_e32 v22, v2
	v_mov_b32_e32 v23, v2
	v_mov_b32_e32 v24, v2
	v_mov_b32_e32 v25, v2
	v_mov_b32_e32 v30, v2
	v_mov_b32_e32 v31, v2
	v_mov_b32_e32 v32, v2
	v_mov_b32_e32 v33, v2
	v_mov_b32_e32 v38, v2
	v_mov_b32_e32 v39, v2
	v_mov_b32_e32 v40, v2
	v_mov_b32_e32 v41, v2
	v_mov_b32_e32 v46, v2
	v_mov_b32_e32 v47, v2
	v_mov_b32_e32 v48, v2
	v_mov_b32_e32 v49, v2
	v_mov_b32_e32 v54, v2
	v_mov_b32_e32 v55, v2
	v_mov_b32_e32 v56, v2
	v_mov_b32_e32 v57, v2
	v_mov_b32_e32 v58, v2
	v_mov_b32_e32 v59, v2
	v_mov_b32_e32 v60, v2
	v_mov_b32_e32 v61, v2
	v_mov_b32_e32 v62, v2
	v_mov_b32_e32 v63, v2
	v_mov_b32_e32 v64, v2
	v_mov_b32_e32 v65, v2
	v_mov_b32_e32 v66, v2
	v_mov_b32_e32 v67, v2
	v_mov_b32_e32 v68, v2
	v_mov_b32_e32 v69, v2
	v_mov_b32_e32 v70, v2
	v_mov_b32_e32 v71, v2
	v_mov_b32_e32 v72, v2
	v_mov_b32_e32 v73, v2
	v_mov_b32_e32 v74, v2
	v_mov_b32_e32 v75, v2
	v_mov_b32_e32 v76, v2
	v_mov_b32_e32 v77, v2
	v_mov_b32_e32 v82, v2
	v_mov_b32_e32 v83, v2
	v_mov_b32_e32 v84, v2
	v_mov_b32_e32 v85, v2
	v_mov_b32_e32 v90, v2
	v_mov_b32_e32 v91, v2
	v_mov_b32_e32 v92, v2
	v_mov_b32_e32 v93, v2
	v_mov_b32_e32 v98, v2
	v_mov_b32_e32 v99, v2
	v_mov_b32_e32 v100, v2
	v_mov_b32_e32 v101, v2
	v_mov_b32_e32 v106, v2
	v_mov_b32_e32 v107, v2
	v_mov_b32_e32 v108, v2
	v_mov_b32_e32 v109, v2
	v_mov_b32_e32 v114, v2
	v_mov_b32_e32 v115, v2
	v_mov_b32_e32 v116, v2
	v_mov_b32_e32 v117, v2
	v_mov_b32_e32 v78, v2
	v_mov_b32_e32 v79, v2
	v_mov_b32_e32 v80, v2
	v_mov_b32_e32 v81, v2
	v_mov_b32_e32 v86, v2
	v_mov_b32_e32 v87, v2
	v_mov_b32_e32 v88, v2
	v_mov_b32_e32 v89, v2
	v_mov_b32_e32 v94, v2
	v_mov_b32_e32 v95, v2
	v_mov_b32_e32 v96, v2
	v_mov_b32_e32 v97, v2
	v_mov_b32_e32 v102, v2
	v_mov_b32_e32 v103, v2
	v_mov_b32_e32 v104, v2
	v_mov_b32_e32 v105, v2
	v_mov_b32_e32 v110, v2
	v_mov_b32_e32 v111, v2
	v_mov_b32_e32 v112, v2
	v_mov_b32_e32 v113, v2
	v_mov_b32_e32 v118, v2
	v_mov_b32_e32 v119, v2
	v_mov_b32_e32 v120, v2
	v_mov_b32_e32 v121, v2
	v_mov_b32_e32 v122, v2
	v_mov_b32_e32 v123, v2
	v_mov_b32_e32 v124, v2
	v_mov_b32_e32 v125, v2
	v_mov_b32_e32 v126, v2
	v_mov_b32_e32 v127, v2
	v_mov_b32_e32 v128, v2
	v_mov_b32_e32 v129, v2
	s_and_b64 s[98:99], exec, s[10:11]
	s_cbranch_scc0 .Lprio_skip_538
	s_setprio 1
.Lprio_skip_538:
.LBB0_538:
	s_add_u32 s24, s22, 0xfffc0080
	s_addc_u32 s25, s23, -1
	s_add_i32 s62, 0, 0x10000
	s_cmp_eq_u32 s75, 12
	s_cselect_b32 s27, s15, s25
	s_cselect_b32 s26, s71, s24
	s_cselect_b32 s25, s13, s74
	s_cselect_b32 s24, s72, s73
	s_add_i32 s76, 0, 0x14000
	v_add_u32_e32 v156, s62, v141
	v_add_u32_e32 v172, s76, v141
	ds_read_b128 v[144:147], v156
	ds_read_b128 v[148:151], v156 offset:1024
	ds_read_b128 v[152:155], v156 offset:2048
	ds_read_b128 v[156:159], v156 offset:3072
	ds_read_b128 v[160:163], v172
	ds_read_b128 v[164:167], v172 offset:1024
	ds_read_b128 v[168:171], v172 offset:2048
	ds_read_b128 v[172:175], v172 offset:3072
	v_lshl_add_u64 v[218:219], s[22:23], 0, v[136:137]
	s_add_i32 m0, s17, 0xc000
	ds_read_b128 v[176:179], v143
	ds_read_b128 v[180:183], v143 offset:1024
	ds_read_b128 v[184:187], v143 offset:2048
	ds_read_b128 v[196:199], v143 offset:3072
	ds_read_b128 v[228:231], v143 offset:4096
	ds_read_b128 v[232:235], v143 offset:5120
	ds_read_b128 v[236:239], v143 offset:6144
	ds_read_b128 v[240:243], v143 offset:7168
	global_load_lds_dwordx4 v[218:219], off
	v_lshl_add_u64 v[218:219], s[22:23], 0, v[138:139]
	s_add_i32 m0, s17, 0xe000
	s_nop 0
	global_load_lds_dwordx4 v[218:219], off
	s_waitcnt vmcnt(8)
	s_waitcnt lgkmcnt(0)
	s_barrier
; #define PG8_STAGE(bufoff, gbase, voff) do { _Pragma("unroll") for (int _i = 0; _i < 2; ++_i) \
;         __builtin_amdgcn_global_load_lds((const unsigned*)((const char*)(gbase) + (voff)[_i]), (PG8_LAS unsigned*)(lds + (bufoff) + ldsw + _i * 8192), 16, 0, 0); } while (0)
; #define PG8_LDA(dst, b, h) do { _Pragma("unroll") for (int m = 0; m < 4; ++m) _Pragma("unroll") for (int k = 0; k < 2; ++k) dst[m][k] = *(const PG8_LAS bf16x8*)(lds + PG8_SA(b, h) + aoff + m * 2048 + k * 1024); } while (0)
; #define PG8_LDB(dst, b, h) do { _Pragma("unroll") for (int n = 0; n < 2; ++n) _Pragma("unroll") for (int k = 0; k < 2; ++k) dst[n][k] = *(const PG8_LAS bf16x8*)(lds + PG8_SB(b, h) + boff + n * 2048 + k * 1024); } while (0)
; #define PG8_MMA(ai, bj, At, Bt) do { __builtin_amdgcn_s_setprio(1); _Pragma("unroll") for (int m = 0; m < 4; ++m) _Pragma("unroll") for (int n = 0; n < 2; ++n) _Pragma("unroll") for (int k = 0; k < 2; ++k) \
;         acc[ai][bj][m][n] = __builtin_amdgcn_mfma_f32_16x16x32_bf16(Bt[n][k], At[m][k], acc[ai][bj][m][n], 0, 0, 0); __builtin_amdgcn_s_setprio(0); } while (0)
; #define PG8_WAIT_V(n) asm volatile("s_waitcnt vmcnt(" #n ")" ::: "memory")
; #define PG8_WAIT_L(n) asm volatile("s_waitcnt lgkmcnt(" #n ")" ::: "memory")
; #define PG8_BAR __builtin_amdgcn_s_barrier()
; #define PG8_SCHED __builtin_amdgcn_sched_barrier(0)
; template <class Epi, class Sched, bool ALIGN_EPI = false, bool SP2 = false>
; __device__ __forceinline__ void gemm_phase(PG8_LAS unsigned char* lds, const Gemm g, const Sched& S, const Epi& E, int tid_in) {
;     ...
;             PG8_LDB(B0, 0, 0); PG8_LDB(B1, 0, 1); PG8_SCHED; PG8_LDA(At, 0, 0); PG8_STAGE(PG8_SA(1, 1), a1 + hstep, voffA);
;             PG8_WAIT_V(8); PG8_WAIT_L(0); PG8_BAR; PG8_MMA(0, 0, At, B0); PG8_MMA(0, 1, At, B1); PG8_BAR; PG8_SCHED;
;             PG8_LDA(At, 0, 1); PG8_STAGE(PG8_SB(0, 0), b2, voffB); PG8_STAGE(PG8_SB(0, 1), b2 + hstep, voffB); PG8_STAGE(PG8_SA(0, 0), a2, voffA);
;             PG8_WAIT_V(8); PG8_WAIT_L(0); PG8_BAR; PG8_MMA(1, 0, At, B0); PG8_MMA(1, 1, At, B1); PG8_BAR; PG8_SCHED;
	s_waitcnt lgkmcnt(0)
	v_mfma_f32_16x16x32_bf16 v[126:129], v[144:147], v[176:179], v[126:129]
	v_mfma_f32_16x16x32_bf16 v[122:125], v[152:155], v[176:179], v[122:125]
	v_mfma_f32_16x16x32_bf16 v[118:121], v[144:147], v[184:187], v[118:121]
	v_mfma_f32_16x16x32_bf16 v[110:113], v[152:155], v[184:187], v[110:113]
	v_mfma_f32_16x16x32_bf16 v[102:105], v[144:147], v[228:231], v[102:105]
	v_mfma_f32_16x16x32_bf16 v[94:97], v[152:155], v[228:231], v[94:97]
	v_mfma_f32_16x16x32_bf16 v[86:89], v[144:147], v[236:239], v[86:89]
	v_mfma_f32_16x16x32_bf16 v[78:81], v[152:155], v[236:239], v[78:81]
	v_mfma_f32_16x16x32_bf16 v[126:129], v[148:151], v[180:183], v[126:129]
	v_mfma_f32_16x16x32_bf16 v[122:125], v[156:159], v[180:183], v[122:125]
	v_mfma_f32_16x16x32_bf16 v[118:121], v[148:151], v[196:199], v[118:121]
	v_mfma_f32_16x16x32_bf16 v[110:113], v[156:159], v[196:199], v[110:113]
	v_mfma_f32_16x16x32_bf16 v[102:105], v[148:151], v[232:235], v[102:105]
	v_mfma_f32_16x16x32_bf16 v[94:97], v[156:159], v[232:235], v[94:97]
	v_mfma_f32_16x16x32_bf16 v[86:89], v[148:151], v[240:243], v[86:89]
	v_mfma_f32_16x16x32_bf16 v[78:81], v[156:159], v[240:243], v[78:81]
	v_mfma_f32_16x16x32_bf16 v[114:117], v[160:163], v[176:179], v[114:117]
	v_mfma_f32_16x16x32_bf16 v[106:109], v[168:171], v[176:179], v[106:109]
	v_mfma_f32_16x16x32_bf16 v[98:101], v[160:163], v[184:187], v[98:101]
	v_mfma_f32_16x16x32_bf16 v[90:93], v[168:171], v[184:187], v[90:93]
	v_mfma_f32_16x16x32_bf16 v[82:85], v[160:163], v[228:231], v[82:85]
	v_mfma_f32_16x16x32_bf16 v[74:77], v[168:171], v[228:231], v[74:77]
	v_mfma_f32_16x16x32_bf16 v[70:73], v[160:163], v[236:239], v[70:73]
	v_mfma_f32_16x16x32_bf16 v[66:69], v[168:171], v[236:239], v[66:69]
	v_mfma_f32_16x16x32_bf16 v[114:117], v[164:167], v[180:183], v[114:117]
	v_mfma_f32_16x16x32_bf16 v[106:109], v[172:175], v[180:183], v[106:109]
	v_mfma_f32_16x16x32_bf16 v[98:101], v[164:167], v[196:199], v[98:101]
	v_mfma_f32_16x16x32_bf16 v[90:93], v[172:175], v[196:199], v[90:93]
	v_mfma_f32_16x16x32_bf16 v[82:85], v[164:167], v[232:235], v[82:85]
	v_mfma_f32_16x16x32_bf16 v[74:77], v[172:175], v[232:235], v[74:77]
	v_mfma_f32_16x16x32_bf16 v[70:73], v[164:167], v[240:243], v[70:73]
	v_mfma_f32_16x16x32_bf16 v[66:69], v[172:175], v[240:243], v[66:69]
	s_barrier
	s_add_i32 s62, s62, s36
	v_lshl_add_u64 v[218:219], s[24:25], 0, v[0:1]
	s_mov_b32 m0, s62
	ds_read_b128 v[176:179], v143 offset:16384
	ds_read_b128 v[180:183], v143 offset:17408
	ds_read_b128 v[184:187], v143 offset:18432
	ds_read_b128 v[196:199], v143 offset:19456
	ds_read_b128 v[228:231], v143 offset:20480
	ds_read_b128 v[232:235], v143 offset:21504
	ds_read_b128 v[236:239], v143 offset:22528
	ds_read_b128 v[240:243], v143 offset:23552
	global_load_lds_dwordx4 v[218:219], off
	s_add_i32 m0, s62, 0x2000
	s_add_u32 s62, s24, 0x40000
	v_lshl_add_u64 v[244:245], s[24:25], 0, v[134:135]
	s_addc_u32 s63, s25, 0
	s_add_i32 s76, s76, s36
	global_load_lds_dwordx4 v[244:245], off
	v_lshl_add_u64 v[246:247], s[62:63], 0, v[0:1]
	s_mov_b32 m0, s76
	v_lshl_add_u64 v[248:249], s[26:27], 0, v[132:133]
	global_load_lds_dwordx4 v[246:247], off
	v_lshl_add_u64 v[246:247], s[62:63], 0, v[134:135]
	s_add_i32 m0, s76, 0x2000
	s_nop 0
	global_load_lds_dwordx4 v[246:247], off
	v_lshl_add_u64 v[246:247], s[26:27], 0, v[130:131]
	s_mov_b32 m0, s17
	s_nop 0
	global_load_lds_dwordx4 v[246:247], off
	s_mov_b32 m0, s37
	s_nop 0
	global_load_lds_dwordx4 v[248:249], off
	s_waitcnt vmcnt(8)
	s_waitcnt lgkmcnt(0)
	s_barrier
	s_waitcnt lgkmcnt(0)
	v_mfma_f32_16x16x32_bf16 v[62:65], v[144:147], v[176:179], v[62:65]
	v_mfma_f32_16x16x32_bf16 v[58:61], v[152:155], v[176:179], v[58:61]
	v_mfma_f32_16x16x32_bf16 v[54:57], v[144:147], v[184:187], v[54:57]
	v_mfma_f32_16x16x32_bf16 v[46:49], v[152:155], v[184:187], v[46:49]
	v_mfma_f32_16x16x32_bf16 v[38:41], v[144:147], v[228:231], v[38:41]
	v_mfma_f32_16x16x32_bf16 v[30:33], v[152:155], v[228:231], v[30:33]
	v_mfma_f32_16x16x32_bf16 v[22:25], v[144:147], v[236:239], v[22:25]
	v_mfma_f32_16x16x32_bf16 v[14:17], v[152:155], v[236:239], v[14:17]
	v_mfma_f32_16x16x32_bf16 v[62:65], v[148:151], v[180:183], v[62:65]
	v_mfma_f32_16x16x32_bf16 v[58:61], v[156:159], v[180:183], v[58:61]
	v_mfma_f32_16x16x32_bf16 v[54:57], v[148:151], v[196:199], v[54:57]
	v_mfma_f32_16x16x32_bf16 v[46:49], v[156:159], v[196:199], v[46:49]
	v_mfma_f32_16x16x32_bf16 v[38:41], v[148:151], v[232:235], v[38:41]
	v_mfma_f32_16x16x32_bf16 v[30:33], v[156:159], v[232:235], v[30:33]
	v_mfma_f32_16x16x32_bf16 v[22:25], v[148:151], v[240:243], v[22:25]
	v_mfma_f32_16x16x32_bf16 v[14:17], v[156:159], v[240:243], v[14:17]
	v_mfma_f32_16x16x32_bf16 v[50:53], v[160:163], v[176:179], v[50:53]
	v_mfma_f32_16x16x32_bf16 v[42:45], v[168:171], v[176:179], v[42:45]
	v_mfma_f32_16x16x32_bf16 v[34:37], v[160:163], v[184:187], v[34:37]
	v_mfma_f32_16x16x32_bf16 v[26:29], v[168:171], v[184:187], v[26:29]
	v_mfma_f32_16x16x32_bf16 v[18:21], v[160:163], v[228:231], v[18:21]
	v_mfma_f32_16x16x32_bf16 v[10:13], v[168:171], v[228:231], v[10:13]
	v_mfma_f32_16x16x32_bf16 v[6:9], v[160:163], v[236:239], v[6:9]
	v_mfma_f32_16x16x32_bf16 v[2:5], v[168:171], v[236:239], v[2:5]
	v_mfma_f32_16x16x32_bf16 v[50:53], v[164:167], v[180:183], v[50:53]
	v_mfma_f32_16x16x32_bf16 v[42:45], v[172:175], v[180:183], v[42:45]
	v_mfma_f32_16x16x32_bf16 v[34:37], v[164:167], v[196:199], v[34:37]
	v_mfma_f32_16x16x32_bf16 v[26:29], v[172:175], v[196:199], v[26:29]
	v_mfma_f32_16x16x32_bf16 v[18:21], v[164:167], v[232:235], v[18:21]
	v_mfma_f32_16x16x32_bf16 v[10:13], v[172:175], v[232:235], v[10:13]
	v_mfma_f32_16x16x32_bf16 v[6:9], v[164:167], v[240:243], v[6:9]
	v_mfma_f32_16x16x32_bf16 v[2:5], v[172:175], v[240:243], v[2:5]
	s_barrier
; #define PG8_STAGE(bufoff, gbase, voff) do { _Pragma("unroll") for (int _i = 0; _i < 2; ++_i) \
;         __builtin_amdgcn_global_load_lds((const unsigned*)((const char*)(gbase) + (voff)[_i]), (PG8_LAS unsigned*)(lds + (bufoff) + ldsw + _i * 8192), 16, 0, 0); } while (0)
; #define PG8_LDA(dst, b, h) do { _Pragma("unroll") for (int m = 0; m < 4; ++m) _Pragma("unroll") for (int k = 0; k < 2; ++k) dst[m][k] = *(const PG8_LAS bf16x8*)(lds + PG8_SA(b, h) + aoff + m * 2048 + k * 1024); } while (0)
; #define PG8_LDB(dst, b, h) do { _Pragma("unroll") for (int n = 0; n < 2; ++n) _Pragma("unroll") for (int k = 0; k < 2; ++k) dst[n][k] = *(const PG8_LAS bf16x8*)(lds + PG8_SB(b, h) + boff + n * 2048 + k * 1024); } while (0)
; #define PG8_MMA(ai, bj, At, Bt) do { __builtin_amdgcn_s_setprio(1); _Pragma("unroll") for (int m = 0; m < 4; ++m) _Pragma("unroll") for (int n = 0; n < 2; ++n) _Pragma("unroll") for (int k = 0; k < 2; ++k) \
;         acc[ai][bj][m][n] = __builtin_amdgcn_mfma_f32_16x16x32_bf16(Bt[n][k], At[m][k], acc[ai][bj][m][n], 0, 0, 0); __builtin_amdgcn_s_setprio(0); } while (0)
; #define PG8_WAIT_V(n) asm volatile("s_waitcnt vmcnt(" #n ")" ::: "memory")
; #define PG8_WAIT_L(n) asm volatile("s_waitcnt lgkmcnt(" #n ")" ::: "memory")
; #define PG8_BAR __builtin_amdgcn_s_barrier()
; #define PG8_SCHED __builtin_amdgcn_sched_barrier(0)
; template <class Epi, class Sched, bool ALIGN_EPI = false, bool SP2 = false>
; __device__ __forceinline__ void gemm_phase(PG8_LAS unsigned char* lds, const Gemm g, const Sched& S, const Epi& E, int tid_in) {
;     ...
;             PG8_LDB(B0, 1, 0); PG8_LDB(B1, 1, 1); PG8_SCHED; PG8_LDA(At, 1, 0); PG8_STAGE(PG8_SA(0, 1), a2 + hstep, voffA);
;             PG8_WAIT_V(8); PG8_WAIT_L(0); PG8_BAR; PG8_MMA(0, 0, At, B0); PG8_MMA(0, 1, At, B1); PG8_BAR; PG8_SCHED;
	s_add_i32 s62, 0, 0x18000
	s_add_i32 s63, 0, 0x1c000
	v_add_u32_e32 v156, s62, v141
	v_add_u32_e32 v172, s63, v141
	ds_read_b128 v[144:147], v156
	ds_read_b128 v[148:151], v156 offset:1024
	ds_read_b128 v[152:155], v156 offset:2048
	ds_read_b128 v[156:159], v156 offset:3072
	ds_read_b128 v[160:163], v172
	ds_read_b128 v[164:167], v172 offset:1024
	ds_read_b128 v[168:171], v172 offset:2048
	ds_read_b128 v[172:175], v172 offset:3072
	s_add_u32 s26, s26, 0x40000
	s_addc_u32 s27, s27, 0
	s_mov_b32 m0, s41
	v_lshl_add_u64 v[250:251], s[26:27], 0, v[130:131]
	ds_read_b128 v[176:179], v143 offset:32768
	ds_read_b128 v[180:183], v143 offset:33792
	ds_read_b128 v[184:187], v143 offset:34816
	ds_read_b128 v[196:199], v143 offset:35840
	ds_read_b128 v[228:231], v143 offset:36864
	ds_read_b128 v[232:235], v143 offset:37888
	ds_read_b128 v[236:239], v143 offset:38912
	ds_read_b128 v[240:243], v143 offset:39936
	global_load_lds_dwordx4 v[250:251], off
	v_lshl_add_u64 v[250:251], s[26:27], 0, v[132:133]
	s_mov_b32 m0, s44
	s_nop 0
	global_load_lds_dwordx4 v[250:251], off
	s_waitcnt vmcnt(8)
	s_waitcnt lgkmcnt(0)
	s_barrier
	s_waitcnt lgkmcnt(0)
	v_mfma_f32_16x16x32_bf16 v[126:129], v[144:147], v[176:179], v[126:129]
	v_mfma_f32_16x16x32_bf16 v[122:125], v[152:155], v[176:179], v[122:125]
	v_mfma_f32_16x16x32_bf16 v[118:121], v[144:147], v[184:187], v[118:121]
	v_mfma_f32_16x16x32_bf16 v[110:113], v[152:155], v[184:187], v[110:113]
	v_mfma_f32_16x16x32_bf16 v[102:105], v[144:147], v[228:231], v[102:105]
	v_mfma_f32_16x16x32_bf16 v[94:97], v[152:155], v[228:231], v[94:97]
	v_mfma_f32_16x16x32_bf16 v[86:89], v[144:147], v[236:239], v[86:89]
	v_mfma_f32_16x16x32_bf16 v[78:81], v[152:155], v[236:239], v[78:81]
	v_mfma_f32_16x16x32_bf16 v[126:129], v[148:151], v[180:183], v[126:129]
	v_mfma_f32_16x16x32_bf16 v[122:125], v[156:159], v[180:183], v[122:125]
	v_mfma_f32_16x16x32_bf16 v[118:121], v[148:151], v[196:199], v[118:121]
	v_mfma_f32_16x16x32_bf16 v[110:113], v[156:159], v[196:199], v[110:113]
	v_mfma_f32_16x16x32_bf16 v[102:105], v[148:151], v[232:235], v[102:105]
	v_mfma_f32_16x16x32_bf16 v[94:97], v[156:159], v[232:235], v[94:97]
	v_mfma_f32_16x16x32_bf16 v[86:89], v[148:151], v[240:243], v[86:89]
	v_mfma_f32_16x16x32_bf16 v[78:81], v[156:159], v[240:243], v[78:81]
	v_mfma_f32_16x16x32_bf16 v[114:117], v[160:163], v[176:179], v[114:117]
	v_mfma_f32_16x16x32_bf16 v[106:109], v[168:171], v[176:179], v[106:109]
	v_mfma_f32_16x16x32_bf16 v[98:101], v[160:163], v[184:187], v[98:101]
	v_mfma_f32_16x16x32_bf16 v[90:93], v[168:171], v[184:187], v[90:93]
	v_mfma_f32_16x16x32_bf16 v[82:85], v[160:163], v[228:231], v[82:85]
	v_mfma_f32_16x16x32_bf16 v[74:77], v[168:171], v[228:231], v[74:77]
	v_mfma_f32_16x16x32_bf16 v[70:73], v[160:163], v[236:239], v[70:73]
	v_mfma_f32_16x16x32_bf16 v[66:69], v[168:171], v[236:239], v[66:69]
	v_mfma_f32_16x16x32_bf16 v[114:117], v[164:167], v[180:183], v[114:117]
	v_mfma_f32_16x16x32_bf16 v[106:109], v[172:175], v[180:183], v[106:109]
	v_mfma_f32_16x16x32_bf16 v[98:101], v[164:167], v[196:199], v[98:101]
	v_mfma_f32_16x16x32_bf16 v[90:93], v[172:175], v[196:199], v[90:93]
	v_mfma_f32_16x16x32_bf16 v[82:85], v[164:167], v[232:235], v[82:85]
	v_mfma_f32_16x16x32_bf16 v[74:77], v[172:175], v[232:235], v[74:77]
	v_mfma_f32_16x16x32_bf16 v[70:73], v[164:167], v[240:243], v[70:73]
	v_mfma_f32_16x16x32_bf16 v[66:69], v[172:175], v[240:243], v[66:69]
	s_barrier
; #define PG8_STAGE(bufoff, gbase, voff) do { _Pragma("unroll") for (int _i = 0; _i < 2; ++_i) \
;         __builtin_amdgcn_global_load_lds((const unsigned*)((const char*)(gbase) + (voff)[_i]), (PG8_LAS unsigned*)(lds + (bufoff) + ldsw + _i * 8192), 16, 0, 0); } while (0)
; #define PG8_LDA(dst, b, h) do { _Pragma("unroll") for (int m = 0; m < 4; ++m) _Pragma("unroll") for (int k = 0; k < 2; ++k) dst[m][k] = *(const PG8_LAS bf16x8*)(lds + PG8_SA(b, h) + aoff + m * 2048 + k * 1024); } while (0)
; #define PG8_BAR __builtin_amdgcn_s_barrier()
; template <class Epi, class Sched, bool ALIGN_EPI = false, bool SP2 = false>
; __device__ __forceinline__ void gemm_phase(PG8_LAS unsigned char* lds, const Gemm g, const Sched& S, const Epi& E, int tid_in) {
;     ...
;             PG8_LDA(At, 1, 1); PG8_STAGE(PG8_SB(1, 0), b3, voffB); PG8_STAGE(PG8_SB(1, 1), b3 + hstep, voffB); PG8_STAGE(PG8_SA(1, 0), a3, voffA);
;             PG8_WAIT_V(8); PG8_WAIT_L(0); PG8_BAR; PG8_MMA(1, 0, At, B0); PG8_MMA(1, 1, At, B1); PG8_BAR; PG8_SCHED;
;             } else {
;             PG8_LDB(B0, 0, 0); PG8_SCHED; PG8_LDA(At, 0, 0); PG8_STAGE(PG8_SA(1, 1), a1 + hstep, voffA);
;             PG8_WAIT_L(8); PG8_BAR; PG8_WAIT_L(0); PG8_MMA(0, 0, At, B0); PG8_BAR; PG8_SCHED;
;             PG8_LDB(B1, 0, 1); PG8_STAGE(PG8_SB(0, 0), b2, voffB);
;             PG8_BAR; PG8_WAIT_L(0); PG8_MMA(0, 1, At, B1); PG8_BAR;
;             PG8_LDA(At, 0, 1); PG8_STAGE(PG8_SA(0, 0), a2, voffA);
;             PG8_BAR; PG8_WAIT_L(0); PG8_MMA(1, 0, At, B0); PG8_BAR; PG8_SCHED;
;             PG8_STAGE(PG8_SB(0, 1), b2 + hstep, voffB);
;             PG8_WAIT_V(6); PG8_BAR; PG8_MMA(1, 1, At, B1); PG8_BAR;
;             PG8_LDB(B0, 1, 0); PG8_SCHED; PG8_LDA(At, 1, 0); PG8_STAGE(PG8_SA(0, 1), a2 + hstep, voffA);
;             PG8_WAIT_L(8); PG8_BAR; PG8_WAIT_L(0); PG8_MMA(0, 0, At, B0); PG8_BAR; PG8_SCHED;
;             PG8_LDB(B1, 1, 1); PG8_STAGE(PG8_SB(1, 0), b3, voffB);
;             PG8_BAR; PG8_WAIT_L(0); PG8_MMA(0, 1, At, B1); PG8_BAR;
;             PG8_LDA(At, 1, 1); PG8_STAGE(PG8_SA(1, 0), a3, voffA);
;             PG8_BAR; PG8_WAIT_L(0); PG8_MMA(1, 0, At, B0); PG8_BAR; PG8_SCHED;
;             PG8_STAGE(PG8_SB(1, 1), b3 + hstep, voffB);
;             PG8_WAIT_V(6); PG8_BAR; PG8_MMA(1, 1, At, B1); PG8_BAR;
;             }
;         }
;         if constexpr (ALIGN_EPI) { if (wr == 0) PG8_BAR; }
	s_add_i32 s26, s62, s36
	v_lshl_add_u64 v[218:219], v[218:219], 0, s[54:55]
	s_mov_b32 m0, s26
	ds_read_b128 v[176:179], v143 offset:49152
	ds_read_b128 v[180:183], v143 offset:50176
	ds_read_b128 v[184:187], v143 offset:51200
	ds_read_b128 v[196:199], v143 offset:52224
	ds_read_b128 v[228:231], v143 offset:53248
	ds_read_b128 v[232:235], v143 offset:54272
	ds_read_b128 v[236:239], v143 offset:55296
	ds_read_b128 v[240:243], v143 offset:56320
	global_load_lds_dwordx4 v[218:219], off
	s_add_i32 m0, s26, 0x2000
	s_add_u32 s24, s24, 0x40080
	v_lshl_add_u64 v[218:219], v[244:245], 0, s[54:55]
	s_addc_u32 s25, s25, 0
	s_add_i32 s26, s63, s36
	global_load_lds_dwordx4 v[218:219], off
	v_lshl_add_u64 v[218:219], s[24:25], 0, v[0:1]
	s_mov_b32 m0, s26
	s_nop 0
	global_load_lds_dwordx4 v[218:219], off
	v_lshl_add_u64 v[218:219], s[24:25], 0, v[134:135]
	s_add_i32 m0, s26, 0x2000
	s_nop 0
	global_load_lds_dwordx4 v[218:219], off
	v_lshl_add_u64 v[218:219], v[246:247], 0, s[54:55]
	s_mov_b32 m0, s46
	s_nop 0
	global_load_lds_dwordx4 v[218:219], off
	v_lshl_add_u64 v[218:219], v[248:249], 0, s[54:55]
	s_mov_b32 m0, s47
	s_nop 0
	global_load_lds_dwordx4 v[218:219], off
	s_waitcnt vmcnt(8)
	s_waitcnt lgkmcnt(0)
	s_barrier
	s_waitcnt lgkmcnt(0)
	v_mfma_f32_16x16x32_bf16 v[62:65], v[144:147], v[176:179], v[62:65]
	v_mfma_f32_16x16x32_bf16 v[58:61], v[152:155], v[176:179], v[58:61]
	v_mfma_f32_16x16x32_bf16 v[54:57], v[144:147], v[184:187], v[54:57]
	v_mfma_f32_16x16x32_bf16 v[46:49], v[152:155], v[184:187], v[46:49]
	v_mfma_f32_16x16x32_bf16 v[38:41], v[144:147], v[228:231], v[38:41]
	v_mfma_f32_16x16x32_bf16 v[30:33], v[152:155], v[228:231], v[30:33]
	v_mfma_f32_16x16x32_bf16 v[22:25], v[144:147], v[236:239], v[22:25]
	v_mfma_f32_16x16x32_bf16 v[14:17], v[152:155], v[236:239], v[14:17]
	v_mfma_f32_16x16x32_bf16 v[62:65], v[148:151], v[180:183], v[62:65]
	v_mfma_f32_16x16x32_bf16 v[58:61], v[156:159], v[180:183], v[58:61]
	v_mfma_f32_16x16x32_bf16 v[54:57], v[148:151], v[196:199], v[54:57]
	v_mfma_f32_16x16x32_bf16 v[46:49], v[156:159], v[196:199], v[46:49]
	v_mfma_f32_16x16x32_bf16 v[38:41], v[148:151], v[232:235], v[38:41]
	v_mfma_f32_16x16x32_bf16 v[30:33], v[156:159], v[232:235], v[30:33]
	v_mfma_f32_16x16x32_bf16 v[22:25], v[148:151], v[240:243], v[22:25]
	v_mfma_f32_16x16x32_bf16 v[14:17], v[156:159], v[240:243], v[14:17]
	v_mfma_f32_16x16x32_bf16 v[50:53], v[160:163], v[176:179], v[50:53]
	v_mfma_f32_16x16x32_bf16 v[42:45], v[168:171], v[176:179], v[42:45]
	v_mfma_f32_16x16x32_bf16 v[34:37], v[160:163], v[184:187], v[34:37]
	v_mfma_f32_16x16x32_bf16 v[26:29], v[168:171], v[184:187], v[26:29]
	v_mfma_f32_16x16x32_bf16 v[18:21], v[160:163], v[228:231], v[18:21]
	v_mfma_f32_16x16x32_bf16 v[10:13], v[168:171], v[228:231], v[10:13]
	v_mfma_f32_16x16x32_bf16 v[6:9], v[160:163], v[236:239], v[6:9]
	v_mfma_f32_16x16x32_bf16 v[2:5], v[168:171], v[236:239], v[2:5]
	v_mfma_f32_16x16x32_bf16 v[50:53], v[164:167], v[180:183], v[50:53]
	v_mfma_f32_16x16x32_bf16 v[42:45], v[172:175], v[180:183], v[42:45]
	v_mfma_f32_16x16x32_bf16 v[34:37], v[164:167], v[196:199], v[34:37]
	v_mfma_f32_16x16x32_bf16 v[26:29], v[172:175], v[196:199], v[26:29]
	v_mfma_f32_16x16x32_bf16 v[18:21], v[164:167], v[232:235], v[18:21]
	v_mfma_f32_16x16x32_bf16 v[10:13], v[172:175], v[232:235], v[10:13]
	v_mfma_f32_16x16x32_bf16 v[6:9], v[164:167], v[240:243], v[6:9]
	v_mfma_f32_16x16x32_bf16 v[2:5], v[172:175], v[240:243], v[2:5]
	s_barrier
	s_add_i32 s75, s75, 2
	s_add_u32 s22, s22, 0x100
	s_addc_u32 s23, s23, 0
	s_add_u32 s73, s73, 0x100
	s_addc_u32 s74, s74, 0
	s_cmp_gt_u32 s75, 13
	s_cbranch_scc0 .LBB0_538
	s_setprio 0
	s_and_b64 vcc, exec, s[10:11]
	s_cbranch_vccz .LBB0_541
	s_barrier

; #define PG8_STAGE(bufoff, gbase, voff) do { _Pragma("unroll") for (int _i = 0; _i < 2; ++_i) \
;         __builtin_amdgcn_global_load_lds((const unsigned*)((const char*)(gbase) + (voff)[_i]), (PG8_LAS unsigned*)(lds + (bufoff) + ldsw + _i * 8192), 16, 0, 0); } while (0)
; #define PG8_LDA(dst, b, h) do { _Pragma("unroll") for (int m = 0; m < 4; ++m) _Pragma("unroll") for (int k = 0; k < 2; ++k) dst[m][k] = *(const PG8_LAS bf16x8*)(lds + PG8_SA(b, h) + aoff + m * 2048 + k * 1024); } while (0)
; #define PG8_LDB(dst, b, h) do { _Pragma("unroll") for (int n = 0; n < 2; ++n) _Pragma("unroll") for (int k = 0; k < 2; ++k) dst[n][k] = *(const PG8_LAS bf16x8*)(lds + PG8_SB(b, h) + boff + n * 2048 + k * 1024); } while (0)
; #define PG8_WAIT_V(n) asm volatile("s_waitcnt vmcnt(" #n ")" ::: "memory")
; #define PG8_WAIT_L(n) asm volatile("s_waitcnt lgkmcnt(" #n ")" ::: "memory")
; #define PG8_BAR __builtin_amdgcn_s_barrier()
; #define PG8_SCHED __builtin_amdgcn_sched_barrier(0)
; template <class Epi, class Sched, bool ALIGN_EPI = false, bool SP2 = false>
; __device__ __forceinline__ void gemm_phase(PG8_LAS unsigned char* lds, const Gemm g, const Sched& S, const Epi& E, int tid_in) {
;     ...
;         const char* nA = has_next ? (const char*)g.A + (size_t)nxt.pm * tstep : cA; const char* nB = has_next ? (const char*)g.Bt + (size_t)nxt.pn * tstep : cB;
;         for (int t = 0; t < nt; t += 2) {
;             const bool last = (t == nt - 2);
;             const char* a1 = cA + (size_t)(t + 1) * kstep;
;             const char* a2 = last ? nA : cA + (size_t)(t + 2) * kstep; const char* b2 = last ? nB : cB + (size_t)(t + 2) * kstep;
;             const char* a3 = a2 + kstep; const char* b3 = b2 + kstep;
;             if (last && has_next) S.a_ready(nxt);
;             if constexpr (SP2) {
;             PG8_LDB(B0, 0, 0); PG8_LDB(B1, 0, 1); PG8_SCHED; PG8_LDA(At, 0, 0); PG8_STAGE(PG8_SA(1, 1), a1 + hstep, voffA);
;             PG8_WAIT_V(8); PG8_WAIT_L(0); PG8_BAR; PG8_MMA(0, 0, At, B0); PG8_MMA(0, 1, At, B1); PG8_BAR; PG8_SCHED;
;     ...
;         for (int a = 0; a < 2; ++a)
; #pragma unroll
;             for (int b = 0; b < 2; ++b)
; #pragma unroll
;                 for (int m = 0; m < 4; ++m)
; #pragma unroll
;                     for (int n = 0; n < 2; ++n) acc[a][b][m][n] = (f32x4){0.f, 0.f, 0.f, 0.f};
.LBB0_678:
	s_ashr_i32 s17, s16, 31
	s_lshl_b64 s[18:19], s[16:17], 19
	s_add_u32 s18, s34, s18
	s_addc_u32 s19, s35, s19
	s_and_b64 s[20:21], s[4:5], exec
	s_cselect_b32 s17, s19, s25
	s_cselect_b32 s46, s18, s24
	s_ashr_i32 s15, s14, 31
	s_lshl_b64 s[20:21], s[14:15], 19
	s_add_u32 s20, s36, s20
	s_addc_u32 s21, s37, s21
	s_and_b64 s[28:29], s[4:5], exec
	s_cselect_b32 s15, s21, s27
	s_cselect_b32 s75, s20, s26
	s_add_u32 s24, s24, 0x40080
	s_addc_u32 s25, s25, 0
	s_add_u32 s76, s26, 0x100
	v_mov_b32_e32 v2, 0
	s_addc_u32 s77, s27, 0
	s_mov_b32 s78, -2
	v_mov_b32_e32 v3, v2
	v_mov_b32_e32 v4, v2
	v_mov_b32_e32 v5, v2
	v_mov_b32_e32 v6, v2
	v_mov_b32_e32 v7, v2
	v_mov_b32_e32 v8, v2
	v_mov_b32_e32 v9, v2
	v_mov_b32_e32 v18, v2
	v_mov_b32_e32 v19, v2
	v_mov_b32_e32 v20, v2
	v_mov_b32_e32 v21, v2
	v_mov_b32_e32 v22, v2
	v_mov_b32_e32 v23, v2
	v_mov_b32_e32 v24, v2
	v_mov_b32_e32 v25, v2
	v_mov_b32_e32 v34, v2
	v_mov_b32_e32 v35, v2
	v_mov_b32_e32 v36, v2
	v_mov_b32_e32 v37, v2
	v_mov_b32_e32 v38, v2
	v_mov_b32_e32 v39, v2
	v_mov_b32_e32 v40, v2
	v_mov_b32_e32 v41, v2
	v_mov_b32_e32 v50, v2
	v_mov_b32_e32 v51, v2
	v_mov_b32_e32 v52, v2
	v_mov_b32_e32 v53, v2
	v_mov_b32_e32 v54, v2
	v_mov_b32_e32 v55, v2
	v_mov_b32_e32 v56, v2
	v_mov_b32_e32 v57, v2
	v_mov_b32_e32 v10, v2
	v_mov_b32_e32 v11, v2
	v_mov_b32_e32 v12, v2
	v_mov_b32_e32 v13, v2
	v_mov_b32_e32 v14, v2
	v_mov_b32_e32 v15, v2
	v_mov_b32_e32 v16, v2
	v_mov_b32_e32 v17, v2
	v_mov_b32_e32 v26, v2
	v_mov_b32_e32 v27, v2
	v_mov_b32_e32 v28, v2
	v_mov_b32_e32 v29, v2
	v_mov_b32_e32 v30, v2
	v_mov_b32_e32 v31, v2
	v_mov_b32_e32 v32, v2
	v_mov_b32_e32 v33, v2
	v_mov_b32_e32 v42, v2
	v_mov_b32_e32 v43, v2
	v_mov_b32_e32 v44, v2
	v_mov_b32_e32 v45, v2
	v_mov_b32_e32 v46, v2
	v_mov_b32_e32 v47, v2
	v_mov_b32_e32 v48, v2
	v_mov_b32_e32 v49, v2
	v_mov_b32_e32 v58, v2
	v_mov_b32_e32 v59, v2
	v_mov_b32_e32 v60, v2
	v_mov_b32_e32 v61, v2
	v_mov_b32_e32 v62, v2
	v_mov_b32_e32 v63, v2
	v_mov_b32_e32 v64, v2
	v_mov_b32_e32 v65, v2
	v_mov_b32_e32 v66, v2
	v_mov_b32_e32 v67, v2
	v_mov_b32_e32 v68, v2
	v_mov_b32_e32 v69, v2
	v_mov_b32_e32 v70, v2
	v_mov_b32_e32 v71, v2
	v_mov_b32_e32 v72, v2
	v_mov_b32_e32 v73, v2
	v_mov_b32_e32 v82, v2
	v_mov_b32_e32 v83, v2
	v_mov_b32_e32 v84, v2
	v_mov_b32_e32 v85, v2
	v_mov_b32_e32 v86, v2
	v_mov_b32_e32 v87, v2
	v_mov_b32_e32 v88, v2
	v_mov_b32_e32 v89, v2
	v_mov_b32_e32 v98, v2
	v_mov_b32_e32 v99, v2
	v_mov_b32_e32 v100, v2
	v_mov_b32_e32 v101, v2
	v_mov_b32_e32 v102, v2
	v_mov_b32_e32 v103, v2
	v_mov_b32_e32 v104, v2
	v_mov_b32_e32 v105, v2
	v_mov_b32_e32 v114, v2
	v_mov_b32_e32 v115, v2
	v_mov_b32_e32 v116, v2
	v_mov_b32_e32 v117, v2
	v_mov_b32_e32 v118, v2
	v_mov_b32_e32 v119, v2
	v_mov_b32_e32 v120, v2
	v_mov_b32_e32 v121, v2
	v_mov_b32_e32 v74, v2
	v_mov_b32_e32 v75, v2
	v_mov_b32_e32 v76, v2
	v_mov_b32_e32 v77, v2
	v_mov_b32_e32 v78, v2
	v_mov_b32_e32 v79, v2
	v_mov_b32_e32 v80, v2
	v_mov_b32_e32 v81, v2
	v_mov_b32_e32 v90, v2
	v_mov_b32_e32 v91, v2
	v_mov_b32_e32 v92, v2
	v_mov_b32_e32 v93, v2
	v_mov_b32_e32 v94, v2
	v_mov_b32_e32 v95, v2
	v_mov_b32_e32 v96, v2
	v_mov_b32_e32 v97, v2
	v_mov_b32_e32 v106, v2
	v_mov_b32_e32 v107, v2
	v_mov_b32_e32 v108, v2
	v_mov_b32_e32 v109, v2
	v_mov_b32_e32 v110, v2
	v_mov_b32_e32 v111, v2
	v_mov_b32_e32 v112, v2
	v_mov_b32_e32 v113, v2
	v_mov_b32_e32 v122, v2
	v_mov_b32_e32 v123, v2
	v_mov_b32_e32 v124, v2
	v_mov_b32_e32 v125, v2
	v_mov_b32_e32 v126, v2
	v_mov_b32_e32 v127, v2
	v_mov_b32_e32 v128, v2
	v_mov_b32_e32 v129, v2
	s_and_b64 s[98:99], exec, s[12:13]
	s_cbranch_scc0 .Lprio_skip_679
	s_setprio 1
.Lprio_skip_679:
.LBB0_679:
	s_add_u32 s26, s24, 0xfffc0080
	s_addc_u32 s27, s25, -1
	s_add_i32 s62, 0, 0x10000
	s_cmp_eq_u32 s78, 12
	s_cselect_b32 s29, s17, s27
	s_cselect_b32 s28, s46, s26
	s_cselect_b32 s27, s15, s77
	s_cselect_b32 s26, s75, s76
	s_add_i32 s79, 0, 0x14000
	v_add_u32_e32 v156, s62, v145
	v_add_u32_e32 v172, s79, v145
	ds_read_b128 v[140:143], v156
	ds_read_b128 v[148:151], v156 offset:1024
	ds_read_b128 v[152:155], v156 offset:2048
	ds_read_b128 v[156:159], v156 offset:3072
	ds_read_b128 v[160:163], v172
	ds_read_b128 v[164:167], v172 offset:1024
	ds_read_b128 v[168:171], v172 offset:2048
	ds_read_b128 v[172:175], v172 offset:3072
	v_lshl_add_u64 v[218:219], s[24:25], 0, v[136:137]
	s_add_i32 m0, s47, 0xc000
	ds_read_b128 v[176:179], v147
	ds_read_b128 v[180:183], v147 offset:1024
	ds_read_b128 v[184:187], v147 offset:2048
	ds_read_b128 v[196:199], v147 offset:3072
	ds_read_b128 v[228:231], v147 offset:4096
	ds_read_b128 v[232:235], v147 offset:5120
	ds_read_b128 v[236:239], v147 offset:6144
	ds_read_b128 v[240:243], v147 offset:7168
	global_load_lds_dwordx4 v[218:219], off
	v_lshl_add_u64 v[218:219], s[24:25], 0, v[138:139]
	s_add_i32 m0, s47, 0xe000
	s_nop 0
	global_load_lds_dwordx4 v[218:219], off
	s_waitcnt vmcnt(8)
	s_waitcnt lgkmcnt(0)
	s_barrier
; #define PG8_STAGE(bufoff, gbase, voff) do { _Pragma("unroll") for (int _i = 0; _i < 2; ++_i) \
;         __builtin_amdgcn_global_load_lds((const unsigned*)((const char*)(gbase) + (voff)[_i]), (PG8_LAS unsigned*)(lds + (bufoff) + ldsw + _i * 8192), 16, 0, 0); } while (0)
; #define PG8_LDA(dst, b, h) do { _Pragma("unroll") for (int m = 0; m < 4; ++m) _Pragma("unroll") for (int k = 0; k < 2; ++k) dst[m][k] = *(const PG8_LAS bf16x8*)(lds + PG8_SA(b, h) + aoff + m * 2048 + k * 1024); } while (0)
; #define PG8_LDB(dst, b, h) do { _Pragma("unroll") for (int n = 0; n < 2; ++n) _Pragma("unroll") for (int k = 0; k < 2; ++k) dst[n][k] = *(const PG8_LAS bf16x8*)(lds + PG8_SB(b, h) + boff + n * 2048 + k * 1024); } while (0)
; #define PG8_MMA(ai, bj, At, Bt) do { __builtin_amdgcn_s_setprio(1); _Pragma("unroll") for (int m = 0; m < 4; ++m) _Pragma("unroll") for (int n = 0; n < 2; ++n) _Pragma("unroll") for (int k = 0; k < 2; ++k) \
;         acc[ai][bj][m][n] = __builtin_amdgcn_mfma_f32_16x16x32_bf16(Bt[n][k], At[m][k], acc[ai][bj][m][n], 0, 0, 0); __builtin_amdgcn_s_setprio(0); } while (0)
; #define PG8_WAIT_V(n) asm volatile("s_waitcnt vmcnt(" #n ")" ::: "memory")
; #define PG8_WAIT_L(n) asm volatile("s_waitcnt lgkmcnt(" #n ")" ::: "memory")
; #define PG8_BAR __builtin_amdgcn_s_barrier()
; #define PG8_SCHED __builtin_amdgcn_sched_barrier(0)
; template <class Epi, class Sched, bool ALIGN_EPI = false, bool SP2 = false>
; __device__ __forceinline__ void gemm_phase(PG8_LAS unsigned char* lds, const Gemm g, const Sched& S, const Epi& E, int tid_in) {
;     ...
;             PG8_LDB(B0, 0, 0); PG8_LDB(B1, 0, 1); PG8_SCHED; PG8_LDA(At, 0, 0); PG8_STAGE(PG8_SA(1, 1), a1 + hstep, voffA);
;             PG8_WAIT_V(8); PG8_WAIT_L(0); PG8_BAR; PG8_MMA(0, 0, At, B0); PG8_MMA(0, 1, At, B1); PG8_BAR; PG8_SCHED;
;             PG8_LDA(At, 0, 1); PG8_STAGE(PG8_SB(0, 0), b2, voffB); PG8_STAGE(PG8_SB(0, 1), b2 + hstep, voffB); PG8_STAGE(PG8_SA(0, 0), a2, voffA);
;             PG8_WAIT_V(8); PG8_WAIT_L(0); PG8_BAR; PG8_MMA(1, 0, At, B0); PG8_MMA(1, 1, At, B1); PG8_BAR; PG8_SCHED;
	s_waitcnt lgkmcnt(0)
	v_mfma_f32_16x16x32_bf16 v[126:129], v[140:143], v[176:179], v[126:129]
	v_mfma_f32_16x16x32_bf16 v[122:125], v[152:155], v[176:179], v[122:125]
	v_mfma_f32_16x16x32_bf16 v[110:113], v[140:143], v[184:187], v[110:113]
	v_mfma_f32_16x16x32_bf16 v[106:109], v[152:155], v[184:187], v[106:109]
	v_mfma_f32_16x16x32_bf16 v[94:97], v[140:143], v[228:231], v[94:97]
	v_mfma_f32_16x16x32_bf16 v[90:93], v[152:155], v[228:231], v[90:93]
	v_mfma_f32_16x16x32_bf16 v[78:81], v[140:143], v[236:239], v[78:81]
	v_mfma_f32_16x16x32_bf16 v[74:77], v[152:155], v[236:239], v[74:77]
	v_mfma_f32_16x16x32_bf16 v[126:129], v[148:151], v[180:183], v[126:129]
	v_mfma_f32_16x16x32_bf16 v[122:125], v[156:159], v[180:183], v[122:125]
	v_mfma_f32_16x16x32_bf16 v[110:113], v[148:151], v[196:199], v[110:113]
	v_mfma_f32_16x16x32_bf16 v[106:109], v[156:159], v[196:199], v[106:109]
	v_mfma_f32_16x16x32_bf16 v[94:97], v[148:151], v[232:235], v[94:97]
	v_mfma_f32_16x16x32_bf16 v[90:93], v[156:159], v[232:235], v[90:93]
	v_mfma_f32_16x16x32_bf16 v[78:81], v[148:151], v[240:243], v[78:81]
	v_mfma_f32_16x16x32_bf16 v[74:77], v[156:159], v[240:243], v[74:77]
	v_mfma_f32_16x16x32_bf16 v[118:121], v[160:163], v[176:179], v[118:121]
	v_mfma_f32_16x16x32_bf16 v[114:117], v[168:171], v[176:179], v[114:117]
	v_mfma_f32_16x16x32_bf16 v[102:105], v[160:163], v[184:187], v[102:105]
	v_mfma_f32_16x16x32_bf16 v[98:101], v[168:171], v[184:187], v[98:101]
	v_mfma_f32_16x16x32_bf16 v[86:89], v[160:163], v[228:231], v[86:89]
	v_mfma_f32_16x16x32_bf16 v[82:85], v[168:171], v[228:231], v[82:85]
	v_mfma_f32_16x16x32_bf16 v[70:73], v[160:163], v[236:239], v[70:73]
	v_mfma_f32_16x16x32_bf16 v[66:69], v[168:171], v[236:239], v[66:69]
	v_mfma_f32_16x16x32_bf16 v[118:121], v[164:167], v[180:183], v[118:121]
	v_mfma_f32_16x16x32_bf16 v[114:117], v[172:175], v[180:183], v[114:117]
	v_mfma_f32_16x16x32_bf16 v[102:105], v[164:167], v[196:199], v[102:105]
	v_mfma_f32_16x16x32_bf16 v[98:101], v[172:175], v[196:199], v[98:101]
	v_mfma_f32_16x16x32_bf16 v[86:89], v[164:167], v[232:235], v[86:89]
	v_mfma_f32_16x16x32_bf16 v[82:85], v[172:175], v[232:235], v[82:85]
	v_mfma_f32_16x16x32_bf16 v[70:73], v[164:167], v[240:243], v[70:73]
	v_mfma_f32_16x16x32_bf16 v[66:69], v[172:175], v[240:243], v[66:69]
	s_barrier
	s_add_i32 s62, s62, s41
	v_lshl_add_u64 v[218:219], s[26:27], 0, v[0:1]
	s_mov_b32 m0, s62
	ds_read_b128 v[176:179], v147 offset:16384
	ds_read_b128 v[180:183], v147 offset:17408
	ds_read_b128 v[184:187], v147 offset:18432
	ds_read_b128 v[196:199], v147 offset:19456
	ds_read_b128 v[228:231], v147 offset:20480
	ds_read_b128 v[232:235], v147 offset:21504
	ds_read_b128 v[236:239], v147 offset:22528
	ds_read_b128 v[240:243], v147 offset:23552
	global_load_lds_dwordx4 v[218:219], off
	s_add_i32 m0, s62, 0x2000
	s_add_u32 s62, s26, 0x40000
	v_lshl_add_u64 v[244:245], s[26:27], 0, v[134:135]
	s_addc_u32 s63, s27, 0
	s_add_i32 s79, s79, s41
	global_load_lds_dwordx4 v[244:245], off
	v_lshl_add_u64 v[246:247], s[62:63], 0, v[0:1]
	s_mov_b32 m0, s79
	v_lshl_add_u64 v[248:249], s[28:29], 0, v[132:133]
	global_load_lds_dwordx4 v[246:247], off
	v_lshl_add_u64 v[246:247], s[62:63], 0, v[134:135]
	s_add_i32 m0, s79, 0x2000
	s_nop 0
	global_load_lds_dwordx4 v[246:247], off
	v_lshl_add_u64 v[246:247], s[28:29], 0, v[130:131]
	s_mov_b32 m0, s47
	s_nop 0
	global_load_lds_dwordx4 v[246:247], off
	s_mov_b32 m0, s48
	s_nop 0
	global_load_lds_dwordx4 v[248:249], off
	s_waitcnt vmcnt(8)
	s_waitcnt lgkmcnt(0)
	s_barrier
	s_waitcnt lgkmcnt(0)
	v_mfma_f32_16x16x32_bf16 v[62:65], v[140:143], v[176:179], v[62:65]
	v_mfma_f32_16x16x32_bf16 v[58:61], v[152:155], v[176:179], v[58:61]
	v_mfma_f32_16x16x32_bf16 v[46:49], v[140:143], v[184:187], v[46:49]
	v_mfma_f32_16x16x32_bf16 v[42:45], v[152:155], v[184:187], v[42:45]
	v_mfma_f32_16x16x32_bf16 v[30:33], v[140:143], v[228:231], v[30:33]
	v_mfma_f32_16x16x32_bf16 v[26:29], v[152:155], v[228:231], v[26:29]
	v_mfma_f32_16x16x32_bf16 v[14:17], v[140:143], v[236:239], v[14:17]
	v_mfma_f32_16x16x32_bf16 v[10:13], v[152:155], v[236:239], v[10:13]
	v_mfma_f32_16x16x32_bf16 v[62:65], v[148:151], v[180:183], v[62:65]
	v_mfma_f32_16x16x32_bf16 v[58:61], v[156:159], v[180:183], v[58:61]
	v_mfma_f32_16x16x32_bf16 v[46:49], v[148:151], v[196:199], v[46:49]
	v_mfma_f32_16x16x32_bf16 v[42:45], v[156:159], v[196:199], v[42:45]
	v_mfma_f32_16x16x32_bf16 v[30:33], v[148:151], v[232:235], v[30:33]
	v_mfma_f32_16x16x32_bf16 v[26:29], v[156:159], v[232:235], v[26:29]
	v_mfma_f32_16x16x32_bf16 v[14:17], v[148:151], v[240:243], v[14:17]
	v_mfma_f32_16x16x32_bf16 v[10:13], v[156:159], v[240:243], v[10:13]
	v_mfma_f32_16x16x32_bf16 v[54:57], v[160:163], v[176:179], v[54:57]
	v_mfma_f32_16x16x32_bf16 v[50:53], v[168:171], v[176:179], v[50:53]
	v_mfma_f32_16x16x32_bf16 v[38:41], v[160:163], v[184:187], v[38:41]
	v_mfma_f32_16x16x32_bf16 v[34:37], v[168:171], v[184:187], v[34:37]
	v_mfma_f32_16x16x32_bf16 v[22:25], v[160:163], v[228:231], v[22:25]
	v_mfma_f32_16x16x32_bf16 v[18:21], v[168:171], v[228:231], v[18:21]
	v_mfma_f32_16x16x32_bf16 v[6:9], v[160:163], v[236:239], v[6:9]
	v_mfma_f32_16x16x32_bf16 v[2:5], v[168:171], v[236:239], v[2:5]
	v_mfma_f32_16x16x32_bf16 v[54:57], v[164:167], v[180:183], v[54:57]
	v_mfma_f32_16x16x32_bf16 v[50:53], v[172:175], v[180:183], v[50:53]
	v_mfma_f32_16x16x32_bf16 v[38:41], v[164:167], v[196:199], v[38:41]
	v_mfma_f32_16x16x32_bf16 v[34:37], v[172:175], v[196:199], v[34:37]
	v_mfma_f32_16x16x32_bf16 v[22:25], v[164:167], v[232:235], v[22:25]
	v_mfma_f32_16x16x32_bf16 v[18:21], v[172:175], v[232:235], v[18:21]
	v_mfma_f32_16x16x32_bf16 v[6:9], v[164:167], v[240:243], v[6:9]
	v_mfma_f32_16x16x32_bf16 v[2:5], v[172:175], v[240:243], v[2:5]
	s_barrier
; #define PG8_STAGE(bufoff, gbase, voff) do { _Pragma("unroll") for (int _i = 0; _i < 2; ++_i) \
;         __builtin_amdgcn_global_load_lds((const unsigned*)((const char*)(gbase) + (voff)[_i]), (PG8_LAS unsigned*)(lds + (bufoff) + ldsw + _i * 8192), 16, 0, 0); } while (0)
; #define PG8_LDA(dst, b, h) do { _Pragma("unroll") for (int m = 0; m < 4; ++m) _Pragma("unroll") for (int k = 0; k < 2; ++k) dst[m][k] = *(const PG8_LAS bf16x8*)(lds + PG8_SA(b, h) + aoff + m * 2048 + k * 1024); } while (0)
; #define PG8_LDB(dst, b, h) do { _Pragma("unroll") for (int n = 0; n < 2; ++n) _Pragma("unroll") for (int k = 0; k < 2; ++k) dst[n][k] = *(const PG8_LAS bf16x8*)(lds + PG8_SB(b, h) + boff + n * 2048 + k * 1024); } while (0)
; #define PG8_MMA(ai, bj, At, Bt) do { __builtin_amdgcn_s_setprio(1); _Pragma("unroll") for (int m = 0; m < 4; ++m) _Pragma("unroll") for (int n = 0; n < 2; ++n) _Pragma("unroll") for (int k = 0; k < 2; ++k) \
;         acc[ai][bj][m][n] = __builtin_amdgcn_mfma_f32_16x16x32_bf16(Bt[n][k], At[m][k], acc[ai][bj][m][n], 0, 0, 0); __builtin_amdgcn_s_setprio(0); } while (0)
; #define PG8_WAIT_V(n) asm volatile("s_waitcnt vmcnt(" #n ")" ::: "memory")
; #define PG8_WAIT_L(n) asm volatile("s_waitcnt lgkmcnt(" #n ")" ::: "memory")
; #define PG8_BAR __builtin_amdgcn_s_barrier()
; #define PG8_SCHED __builtin_amdgcn_sched_barrier(0)
; template <class Epi, class Sched, bool ALIGN_EPI = false, bool SP2 = false>
; __device__ __forceinline__ void gemm_phase(PG8_LAS unsigned char* lds, const Gemm g, const Sched& S, const Epi& E, int tid_in) {
;     ...
;             PG8_LDB(B0, 1, 0); PG8_LDB(B1, 1, 1); PG8_SCHED; PG8_LDA(At, 1, 0); PG8_STAGE(PG8_SA(0, 1), a2 + hstep, voffA);
;             PG8_WAIT_V(8); PG8_WAIT_L(0); PG8_BAR; PG8_MMA(0, 0, At, B0); PG8_MMA(0, 1, At, B1); PG8_BAR; PG8_SCHED;
	s_add_i32 s62, 0, 0x18000
	s_add_i32 s63, 0, 0x1c000
	v_add_u32_e32 v156, s62, v145
	v_add_u32_e32 v172, s63, v145
	ds_read_b128 v[140:143], v156
	ds_read_b128 v[148:151], v156 offset:1024
	ds_read_b128 v[152:155], v156 offset:2048
	ds_read_b128 v[156:159], v156 offset:3072
	ds_read_b128 v[160:163], v172
	ds_read_b128 v[164:167], v172 offset:1024
	ds_read_b128 v[168:171], v172 offset:2048
	ds_read_b128 v[172:175], v172 offset:3072
	s_add_u32 s28, s28, 0x40000
	s_addc_u32 s29, s29, 0
	s_mov_b32 m0, s49
	v_lshl_add_u64 v[250:251], s[28:29], 0, v[130:131]
	ds_read_b128 v[176:179], v147 offset:32768
	ds_read_b128 v[180:183], v147 offset:33792
	ds_read_b128 v[184:187], v147 offset:34816
	ds_read_b128 v[196:199], v147 offset:35840
	ds_read_b128 v[228:231], v147 offset:36864
	ds_read_b128 v[232:235], v147 offset:37888
	ds_read_b128 v[236:239], v147 offset:38912
	ds_read_b128 v[240:243], v147 offset:39936
	global_load_lds_dwordx4 v[250:251], off
	v_lshl_add_u64 v[250:251], s[28:29], 0, v[132:133]
	s_mov_b32 m0, s70
	s_nop 0
	global_load_lds_dwordx4 v[250:251], off
	s_waitcnt vmcnt(8)
	s_waitcnt lgkmcnt(0)
	s_barrier
	s_waitcnt lgkmcnt(0)
	v_mfma_f32_16x16x32_bf16 v[126:129], v[140:143], v[176:179], v[126:129]
	v_mfma_f32_16x16x32_bf16 v[122:125], v[152:155], v[176:179], v[122:125]
	v_mfma_f32_16x16x32_bf16 v[110:113], v[140:143], v[184:187], v[110:113]
	v_mfma_f32_16x16x32_bf16 v[106:109], v[152:155], v[184:187], v[106:109]
	v_mfma_f32_16x16x32_bf16 v[94:97], v[140:143], v[228:231], v[94:97]
	v_mfma_f32_16x16x32_bf16 v[90:93], v[152:155], v[228:231], v[90:93]
	v_mfma_f32_16x16x32_bf16 v[78:81], v[140:143], v[236:239], v[78:81]
	v_mfma_f32_16x16x32_bf16 v[74:77], v[152:155], v[236:239], v[74:77]
	v_mfma_f32_16x16x32_bf16 v[126:129], v[148:151], v[180:183], v[126:129]
	v_mfma_f32_16x16x32_bf16 v[122:125], v[156:159], v[180:183], v[122:125]
	v_mfma_f32_16x16x32_bf16 v[110:113], v[148:151], v[196:199], v[110:113]
	v_mfma_f32_16x16x32_bf16 v[106:109], v[156:159], v[196:199], v[106:109]
	v_mfma_f32_16x16x32_bf16 v[94:97], v[148:151], v[232:235], v[94:97]
	v_mfma_f32_16x16x32_bf16 v[90:93], v[156:159], v[232:235], v[90:93]
	v_mfma_f32_16x16x32_bf16 v[78:81], v[148:151], v[240:243], v[78:81]
	v_mfma_f32_16x16x32_bf16 v[74:77], v[156:159], v[240:243], v[74:77]
	v_mfma_f32_16x16x32_bf16 v[118:121], v[160:163], v[176:179], v[118:121]
	v_mfma_f32_16x16x32_bf16 v[114:117], v[168:171], v[176:179], v[114:117]
	v_mfma_f32_16x16x32_bf16 v[102:105], v[160:163], v[184:187], v[102:105]
	v_mfma_f32_16x16x32_bf16 v[98:101], v[168:171], v[184:187], v[98:101]
	v_mfma_f32_16x16x32_bf16 v[86:89], v[160:163], v[228:231], v[86:89]
	v_mfma_f32_16x16x32_bf16 v[82:85], v[168:171], v[228:231], v[82:85]
	v_mfma_f32_16x16x32_bf16 v[70:73], v[160:163], v[236:239], v[70:73]
	v_mfma_f32_16x16x32_bf16 v[66:69], v[168:171], v[236:239], v[66:69]
	v_mfma_f32_16x16x32_bf16 v[118:121], v[164:167], v[180:183], v[118:121]
	v_mfma_f32_16x16x32_bf16 v[114:117], v[172:175], v[180:183], v[114:117]
	v_mfma_f32_16x16x32_bf16 v[102:105], v[164:167], v[196:199], v[102:105]
	v_mfma_f32_16x16x32_bf16 v[98:101], v[172:175], v[196:199], v[98:101]
	v_mfma_f32_16x16x32_bf16 v[86:89], v[164:167], v[232:235], v[86:89]
	v_mfma_f32_16x16x32_bf16 v[82:85], v[172:175], v[232:235], v[82:85]
	v_mfma_f32_16x16x32_bf16 v[70:73], v[164:167], v[240:243], v[70:73]
	v_mfma_f32_16x16x32_bf16 v[66:69], v[172:175], v[240:243], v[66:69]
	s_barrier
; #define PG8_STAGE(bufoff, gbase, voff) do { _Pragma("unroll") for (int _i = 0; _i < 2; ++_i) \
;         __builtin_amdgcn_global_load_lds((const unsigned*)((const char*)(gbase) + (voff)[_i]), (PG8_LAS unsigned*)(lds + (bufoff) + ldsw + _i * 8192), 16, 0, 0); } while (0)
; #define PG8_LDA(dst, b, h) do { _Pragma("unroll") for (int m = 0; m < 4; ++m) _Pragma("unroll") for (int k = 0; k < 2; ++k) dst[m][k] = *(const PG8_LAS bf16x8*)(lds + PG8_SA(b, h) + aoff + m * 2048 + k * 1024); } while (0)
; #define PG8_BAR __builtin_amdgcn_s_barrier()
; template <class Epi, class Sched, bool ALIGN_EPI = false, bool SP2 = false>
; __device__ __forceinline__ void gemm_phase(PG8_LAS unsigned char* lds, const Gemm g, const Sched& S, const Epi& E, int tid_in) {
;     ...
;             PG8_LDA(At, 1, 1); PG8_STAGE(PG8_SB(1, 0), b3, voffB); PG8_STAGE(PG8_SB(1, 1), b3 + hstep, voffB); PG8_STAGE(PG8_SA(1, 0), a3, voffA);
;             PG8_WAIT_V(8); PG8_WAIT_L(0); PG8_BAR; PG8_MMA(1, 0, At, B0); PG8_MMA(1, 1, At, B1); PG8_BAR; PG8_SCHED;
;             } else {
;             PG8_LDB(B0, 0, 0); PG8_SCHED; PG8_LDA(At, 0, 0); PG8_STAGE(PG8_SA(1, 1), a1 + hstep, voffA);
;             PG8_WAIT_L(8); PG8_BAR; PG8_WAIT_L(0); PG8_MMA(0, 0, At, B0); PG8_BAR; PG8_SCHED;
;             PG8_LDB(B1, 0, 1); PG8_STAGE(PG8_SB(0, 0), b2, voffB);
;             PG8_BAR; PG8_WAIT_L(0); PG8_MMA(0, 1, At, B1); PG8_BAR;
;             PG8_LDA(At, 0, 1); PG8_STAGE(PG8_SA(0, 0), a2, voffA);
;             PG8_BAR; PG8_WAIT_L(0); PG8_MMA(1, 0, At, B0); PG8_BAR; PG8_SCHED;
;             PG8_STAGE(PG8_SB(0, 1), b2 + hstep, voffB);
;             PG8_WAIT_V(6); PG8_BAR; PG8_MMA(1, 1, At, B1); PG8_BAR;
;             PG8_LDB(B0, 1, 0); PG8_SCHED; PG8_LDA(At, 1, 0); PG8_STAGE(PG8_SA(0, 1), a2 + hstep, voffA);
;             PG8_WAIT_L(8); PG8_BAR; PG8_WAIT_L(0); PG8_MMA(0, 0, At, B0); PG8_BAR; PG8_SCHED;
;             PG8_LDB(B1, 1, 1); PG8_STAGE(PG8_SB(1, 0), b3, voffB);
;             PG8_BAR; PG8_WAIT_L(0); PG8_MMA(0, 1, At, B1); PG8_BAR;
;             PG8_LDA(At, 1, 1); PG8_STAGE(PG8_SA(1, 0), a3, voffA);
;             PG8_BAR; PG8_WAIT_L(0); PG8_MMA(1, 0, At, B0); PG8_BAR; PG8_SCHED;
;             PG8_STAGE(PG8_SB(1, 1), b3 + hstep, voffB);
;             PG8_WAIT_V(6); PG8_BAR; PG8_MMA(1, 1, At, B1); PG8_BAR;
;             }
;         }
;         if constexpr (ALIGN_EPI) { if (wr == 0) PG8_BAR; }
	s_add_i32 s28, s62, s41
	v_lshl_add_u64 v[218:219], v[218:219], 0, s[54:55]
	s_mov_b32 m0, s28
	ds_read_b128 v[176:179], v147 offset:49152
	ds_read_b128 v[180:183], v147 offset:50176
	ds_read_b128 v[184:187], v147 offset:51200
	ds_read_b128 v[196:199], v147 offset:52224
	ds_read_b128 v[228:231], v147 offset:53248
	ds_read_b128 v[232:235], v147 offset:54272
	ds_read_b128 v[236:239], v147 offset:55296
	ds_read_b128 v[240:243], v147 offset:56320
	global_load_lds_dwordx4 v[218:219], off
	s_add_i32 m0, s28, 0x2000
	s_add_u32 s26, s26, 0x40080
	v_lshl_add_u64 v[218:219], v[244:245], 0, s[54:55]
	s_addc_u32 s27, s27, 0
	s_add_i32 s28, s63, s41
	global_load_lds_dwordx4 v[218:219], off
	v_lshl_add_u64 v[218:219], s[26:27], 0, v[0:1]
	s_mov_b32 m0, s28
	s_nop 0
	global_load_lds_dwordx4 v[218:219], off
	v_lshl_add_u64 v[218:219], s[26:27], 0, v[134:135]
	s_add_i32 m0, s28, 0x2000
	s_nop 0
	global_load_lds_dwordx4 v[218:219], off
	v_lshl_add_u64 v[218:219], v[246:247], 0, s[54:55]
	s_mov_b32 m0, s71
	s_nop 0
	global_load_lds_dwordx4 v[218:219], off
	v_lshl_add_u64 v[218:219], v[248:249], 0, s[54:55]
	s_mov_b32 m0, s72
	s_nop 0
	global_load_lds_dwordx4 v[218:219], off
	s_waitcnt vmcnt(8)
	s_waitcnt lgkmcnt(0)
	s_barrier
	s_waitcnt lgkmcnt(0)
	v_mfma_f32_16x16x32_bf16 v[62:65], v[140:143], v[176:179], v[62:65]
	v_mfma_f32_16x16x32_bf16 v[58:61], v[152:155], v[176:179], v[58:61]
	v_mfma_f32_16x16x32_bf16 v[46:49], v[140:143], v[184:187], v[46:49]
	v_mfma_f32_16x16x32_bf16 v[42:45], v[152:155], v[184:187], v[42:45]
	v_mfma_f32_16x16x32_bf16 v[30:33], v[140:143], v[228:231], v[30:33]
	v_mfma_f32_16x16x32_bf16 v[26:29], v[152:155], v[228:231], v[26:29]
	v_mfma_f32_16x16x32_bf16 v[14:17], v[140:143], v[236:239], v[14:17]
	v_mfma_f32_16x16x32_bf16 v[10:13], v[152:155], v[236:239], v[10:13]
	v_mfma_f32_16x16x32_bf16 v[62:65], v[148:151], v[180:183], v[62:65]
	v_mfma_f32_16x16x32_bf16 v[58:61], v[156:159], v[180:183], v[58:61]
	v_mfma_f32_16x16x32_bf16 v[46:49], v[148:151], v[196:199], v[46:49]
	v_mfma_f32_16x16x32_bf16 v[42:45], v[156:159], v[196:199], v[42:45]
	v_mfma_f32_16x16x32_bf16 v[30:33], v[148:151], v[232:235], v[30:33]
	v_mfma_f32_16x16x32_bf16 v[26:29], v[156:159], v[232:235], v[26:29]
	v_mfma_f32_16x16x32_bf16 v[14:17], v[148:151], v[240:243], v[14:17]
	v_mfma_f32_16x16x32_bf16 v[10:13], v[156:159], v[240:243], v[10:13]
	v_mfma_f32_16x16x32_bf16 v[54:57], v[160:163], v[176:179], v[54:57]
	v_mfma_f32_16x16x32_bf16 v[50:53], v[168:171], v[176:179], v[50:53]
	v_mfma_f32_16x16x32_bf16 v[38:41], v[160:163], v[184:187], v[38:41]
	v_mfma_f32_16x16x32_bf16 v[34:37], v[168:171], v[184:187], v[34:37]
	v_mfma_f32_16x16x32_bf16 v[22:25], v[160:163], v[228:231], v[22:25]
	v_mfma_f32_16x16x32_bf16 v[18:21], v[168:171], v[228:231], v[18:21]
	v_mfma_f32_16x16x32_bf16 v[6:9], v[160:163], v[236:239], v[6:9]
	v_mfma_f32_16x16x32_bf16 v[2:5], v[168:171], v[236:239], v[2:5]
	v_mfma_f32_16x16x32_bf16 v[54:57], v[164:167], v[180:183], v[54:57]
	v_mfma_f32_16x16x32_bf16 v[50:53], v[172:175], v[180:183], v[50:53]
	v_mfma_f32_16x16x32_bf16 v[38:41], v[164:167], v[196:199], v[38:41]
	v_mfma_f32_16x16x32_bf16 v[34:37], v[172:175], v[196:199], v[34:37]
	v_mfma_f32_16x16x32_bf16 v[22:25], v[164:167], v[232:235], v[22:25]
	v_mfma_f32_16x16x32_bf16 v[18:21], v[172:175], v[232:235], v[18:21]
	v_mfma_f32_16x16x32_bf16 v[6:9], v[164:167], v[240:243], v[6:9]
	v_mfma_f32_16x16x32_bf16 v[2:5], v[172:175], v[240:243], v[2:5]
	s_barrier
	s_add_i32 s78, s78, 2
	s_add_u32 s24, s24, 0x100
	s_addc_u32 s25, s25, 0
	s_add_u32 s76, s76, 0x100
	s_addc_u32 s77, s77, 0
	s_cmp_gt_u32 s78, 13
	s_cbranch_scc0 .LBB0_679
	s_setprio 0
	s_and_b64 vcc, exec, s[12:13]
	s_cbranch_vccz .LBB0_682
	s_barrier

; #define PG8_STAGE(bufoff, gbase, voff) do { _Pragma("unroll") for (int _i = 0; _i < 2; ++_i) \
;         __builtin_amdgcn_global_load_lds((const unsigned*)((const char*)(gbase) + (voff)[_i]), (PG8_LAS unsigned*)(lds + (bufoff) + ldsw + _i * 8192), 16, 0, 0); } while (0)
; #define PG8_LDA(dst, b, h) do { _Pragma("unroll") for (int m = 0; m < 4; ++m) _Pragma("unroll") for (int k = 0; k < 2; ++k) dst[m][k] = *(const PG8_LAS bf16x8*)(lds + PG8_SA(b, h) + aoff + m * 2048 + k * 1024); } while (0)
; #define PG8_LDB(dst, b, h) do { _Pragma("unroll") for (int n = 0; n < 2; ++n) _Pragma("unroll") for (int k = 0; k < 2; ++k) dst[n][k] = *(const PG8_LAS bf16x8*)(lds + PG8_SB(b, h) + boff + n * 2048 + k * 1024); } while (0)
; #define PG8_WAIT_V(n) asm volatile("s_waitcnt vmcnt(" #n ")" ::: "memory")
; #define PG8_WAIT_L(n) asm volatile("s_waitcnt lgkmcnt(" #n ")" ::: "memory")
; #define PG8_BAR __builtin_amdgcn_s_barrier()
; #define PG8_SCHED __builtin_amdgcn_sched_barrier(0)
; template <class Epi, class Sched, bool ALIGN_EPI = false, bool SP2 = false>
; __device__ __forceinline__ void gemm_phase(PG8_LAS unsigned char* lds, const Gemm g, const Sched& S, const Epi& E, int tid_in) {
;     ...
;         const char* nA = has_next ? (const char*)g.A + (size_t)nxt.pm * tstep : cA; const char* nB = has_next ? (const char*)g.Bt + (size_t)nxt.pn * tstep : cB;
;         for (int t = 0; t < nt; t += 2) {
;             const bool last = (t == nt - 2);
;             const char* a1 = cA + (size_t)(t + 1) * kstep;
;             const char* a2 = last ? nA : cA + (size_t)(t + 2) * kstep; const char* b2 = last ? nB : cB + (size_t)(t + 2) * kstep;
;             const char* a3 = a2 + kstep; const char* b3 = b2 + kstep;
;             if (last && has_next) S.a_ready(nxt);
;             if constexpr (SP2) {
;             PG8_LDB(B0, 0, 0); PG8_LDB(B1, 0, 1); PG8_SCHED; PG8_LDA(At, 0, 0); PG8_STAGE(PG8_SA(1, 1), a1 + hstep, voffA);
;             PG8_WAIT_V(8); PG8_WAIT_L(0); PG8_BAR; PG8_MMA(0, 0, At, B0); PG8_MMA(0, 1, At, B1); PG8_BAR; PG8_SCHED;
;     ...
;         for (int a = 0; a < 2; ++a)
; #pragma unroll
;             for (int b = 0; b < 2; ++b)
; #pragma unroll
;                 for (int m = 0; m < 4; ++m)
; #pragma unroll
;                     for (int n = 0; n < 2; ++n) acc[a][b][m][n] = (f32x4){0.f, 0.f, 0.f, 0.f};
.LBB0_754:
	s_ashr_i32 s15, s14, 31
	s_lshl_b64 s[18:19], s[14:15], 21
	s_add_u32 s18, s30, s18
	s_addc_u32 s19, s31, s19
	s_and_b64 s[20:21], s[4:5], exec
	s_cselect_b32 s15, s19, s23
	s_cselect_b32 s72, s18, s22
	s_ashr_i32 s13, s12, 31
	s_lshl_b64 s[20:21], s[12:13], 21
	s_add_u32 s20, s34, s20
	s_addc_u32 s21, s35, s21
	s_and_b64 s[26:27], s[4:5], exec
	s_cselect_b32 s13, s21, s25
	s_cselect_b32 s73, s20, s24
	s_add_u32 s22, s22, 0x100080
	s_addc_u32 s23, s23, 0
	s_add_u32 s74, s24, 0x100
	v_mov_b32_e32 v2, 0
	s_addc_u32 s75, s25, 0
	s_mov_b32 s76, -2
	v_mov_b32_e32 v3, v2
	v_mov_b32_e32 v4, v2
	v_mov_b32_e32 v5, v2
	v_mov_b32_e32 v6, v2
	v_mov_b32_e32 v7, v2
	v_mov_b32_e32 v8, v2
	v_mov_b32_e32 v9, v2
	v_mov_b32_e32 v10, v2
	v_mov_b32_e32 v11, v2
	v_mov_b32_e32 v12, v2
	v_mov_b32_e32 v13, v2
	v_mov_b32_e32 v18, v2
	v_mov_b32_e32 v19, v2
	v_mov_b32_e32 v20, v2
	v_mov_b32_e32 v21, v2
	v_mov_b32_e32 v26, v2
	v_mov_b32_e32 v27, v2
	v_mov_b32_e32 v28, v2
	v_mov_b32_e32 v29, v2
	v_mov_b32_e32 v34, v2
	v_mov_b32_e32 v35, v2
	v_mov_b32_e32 v36, v2
	v_mov_b32_e32 v37, v2
	v_mov_b32_e32 v42, v2
	v_mov_b32_e32 v43, v2
	v_mov_b32_e32 v44, v2
	v_mov_b32_e32 v45, v2
	v_mov_b32_e32 v50, v2
	v_mov_b32_e32 v51, v2
	v_mov_b32_e32 v52, v2
	v_mov_b32_e32 v53, v2
	v_mov_b32_e32 v14, v2
	v_mov_b32_e32 v15, v2
	v_mov_b32_e32 v16, v2
	v_mov_b32_e32 v17, v2
	v_mov_b32_e32 v22, v2
	v_mov_b32_e32 v23, v2
	v_mov_b32_e32 v24, v2
	v_mov_b32_e32 v25, v2
	v_mov_b32_e32 v30, v2
	v_mov_b32_e32 v31, v2
	v_mov_b32_e32 v32, v2
	v_mov_b32_e32 v33, v2
	v_mov_b32_e32 v38, v2
	v_mov_b32_e32 v39, v2
	v_mov_b32_e32 v40, v2
	v_mov_b32_e32 v41, v2
	v_mov_b32_e32 v46, v2
	v_mov_b32_e32 v47, v2
	v_mov_b32_e32 v48, v2
	v_mov_b32_e32 v49, v2
	v_mov_b32_e32 v54, v2
	v_mov_b32_e32 v55, v2
	v_mov_b32_e32 v56, v2
	v_mov_b32_e32 v57, v2
	v_mov_b32_e32 v58, v2
	v_mov_b32_e32 v59, v2
	v_mov_b32_e32 v60, v2
	v_mov_b32_e32 v61, v2
	v_mov_b32_e32 v62, v2
	v_mov_b32_e32 v63, v2
	v_mov_b32_e32 v64, v2
	v_mov_b32_e32 v65, v2
	v_mov_b32_e32 v66, v2
	v_mov_b32_e32 v67, v2
	v_mov_b32_e32 v68, v2
	v_mov_b32_e32 v69, v2
	v_mov_b32_e32 v70, v2
	v_mov_b32_e32 v71, v2
	v_mov_b32_e32 v72, v2
	v_mov_b32_e32 v73, v2
	v_mov_b32_e32 v74, v2
	v_mov_b32_e32 v75, v2
	v_mov_b32_e32 v76, v2
	v_mov_b32_e32 v77, v2
	v_mov_b32_e32 v82, v2
	v_mov_b32_e32 v83, v2
	v_mov_b32_e32 v84, v2
	v_mov_b32_e32 v85, v2
	v_mov_b32_e32 v90, v2
	v_mov_b32_e32 v91, v2
	v_mov_b32_e32 v92, v2
	v_mov_b32_e32 v93, v2
	v_mov_b32_e32 v98, v2
	v_mov_b32_e32 v99, v2
	v_mov_b32_e32 v100, v2
	v_mov_b32_e32 v101, v2
	v_mov_b32_e32 v106, v2
	v_mov_b32_e32 v107, v2
	v_mov_b32_e32 v108, v2
	v_mov_b32_e32 v109, v2
	v_mov_b32_e32 v114, v2
	v_mov_b32_e32 v115, v2
	v_mov_b32_e32 v116, v2
	v_mov_b32_e32 v117, v2
	v_mov_b32_e32 v78, v2
	v_mov_b32_e32 v79, v2
	v_mov_b32_e32 v80, v2
	v_mov_b32_e32 v81, v2
	v_mov_b32_e32 v86, v2
	v_mov_b32_e32 v87, v2
	v_mov_b32_e32 v88, v2
	v_mov_b32_e32 v89, v2
	v_mov_b32_e32 v94, v2
	v_mov_b32_e32 v95, v2
	v_mov_b32_e32 v96, v2
	v_mov_b32_e32 v97, v2
	v_mov_b32_e32 v102, v2
	v_mov_b32_e32 v103, v2
	v_mov_b32_e32 v104, v2
	v_mov_b32_e32 v105, v2
	v_mov_b32_e32 v110, v2
	v_mov_b32_e32 v111, v2
	v_mov_b32_e32 v112, v2
	v_mov_b32_e32 v113, v2
	v_mov_b32_e32 v118, v2
	v_mov_b32_e32 v119, v2
	v_mov_b32_e32 v120, v2
	v_mov_b32_e32 v121, v2
	v_mov_b32_e32 v122, v2
	v_mov_b32_e32 v123, v2
	v_mov_b32_e32 v124, v2
	v_mov_b32_e32 v125, v2
	v_mov_b32_e32 v126, v2
	v_mov_b32_e32 v127, v2
	v_mov_b32_e32 v128, v2
	v_mov_b32_e32 v129, v2
	s_and_b64 s[98:99], exec, s[10:11]
	s_cbranch_scc0 .Lprio_skip_755
	s_setprio 1
.Lprio_skip_755:
.LBB0_755:
	s_add_u32 s24, s22, 0xfff00080
	s_addc_u32 s25, s23, -1
	s_add_i32 s62, 0, 0x10000
	s_cmp_eq_u32 s76, 60
	s_cselect_b32 s27, s15, s25
	s_cselect_b32 s26, s72, s24
	s_cselect_b32 s25, s13, s75
	s_cselect_b32 s24, s73, s74
	s_add_i32 s77, 0, 0x14000
	v_add_u32_e32 v156, s62, v141
	v_add_u32_e32 v172, s77, v141
	ds_read_b128 v[144:147], v156
	ds_read_b128 v[148:151], v156 offset:1024
	ds_read_b128 v[152:155], v156 offset:2048
	ds_read_b128 v[156:159], v156 offset:3072
	ds_read_b128 v[160:163], v172
	ds_read_b128 v[164:167], v172 offset:1024
	ds_read_b128 v[168:171], v172 offset:2048
	ds_read_b128 v[172:175], v172 offset:3072
	v_lshl_add_u64 v[218:219], s[22:23], 0, v[136:137]
	s_add_i32 m0, s17, 0xc000
	ds_read_b128 v[176:179], v143
	ds_read_b128 v[180:183], v143 offset:1024
	ds_read_b128 v[184:187], v143 offset:2048
	ds_read_b128 v[196:199], v143 offset:3072
	ds_read_b128 v[228:231], v143 offset:4096
	ds_read_b128 v[232:235], v143 offset:5120
	ds_read_b128 v[236:239], v143 offset:6144
	ds_read_b128 v[240:243], v143 offset:7168
	global_load_lds_dwordx4 v[218:219], off
	v_lshl_add_u64 v[218:219], s[22:23], 0, v[138:139]
	s_add_i32 m0, s17, 0xe000
	s_nop 0
	global_load_lds_dwordx4 v[218:219], off
	s_waitcnt vmcnt(8)
	s_waitcnt lgkmcnt(0)
	s_barrier
; #define PG8_STAGE(bufoff, gbase, voff) do { _Pragma("unroll") for (int _i = 0; _i < 2; ++_i) \
;         __builtin_amdgcn_global_load_lds((const unsigned*)((const char*)(gbase) + (voff)[_i]), (PG8_LAS unsigned*)(lds + (bufoff) + ldsw + _i * 8192), 16, 0, 0); } while (0)
; #define PG8_LDA(dst, b, h) do { _Pragma("unroll") for (int m = 0; m < 4; ++m) _Pragma("unroll") for (int k = 0; k < 2; ++k) dst[m][k] = *(const PG8_LAS bf16x8*)(lds + PG8_SA(b, h) + aoff + m * 2048 + k * 1024); } while (0)
; #define PG8_MMA(ai, bj, At, Bt) do { __builtin_amdgcn_s_setprio(1); _Pragma("unroll") for (int m = 0; m < 4; ++m) _Pragma("unroll") for (int n = 0; n < 2; ++n) _Pragma("unroll") for (int k = 0; k < 2; ++k) \
;         acc[ai][bj][m][n] = __builtin_amdgcn_mfma_f32_16x16x32_bf16(Bt[n][k], At[m][k], acc[ai][bj][m][n], 0, 0, 0); __builtin_amdgcn_s_setprio(0); } while (0)
; #define PG8_WAIT_V(n) asm volatile("s_waitcnt vmcnt(" #n ")" ::: "memory")
; #define PG8_WAIT_L(n) asm volatile("s_waitcnt lgkmcnt(" #n ")" ::: "memory")
; #define PG8_BAR __builtin_amdgcn_s_barrier()
; #define PG8_SCHED __builtin_amdgcn_sched_barrier(0)
; template <class Epi, class Sched, bool ALIGN_EPI = false, bool SP2 = false>
; __device__ __forceinline__ void gemm_phase(PG8_LAS unsigned char* lds, const Gemm g, const Sched& S, const Epi& E, int tid_in) {
;     ...
;             PG8_WAIT_V(8); PG8_WAIT_L(0); PG8_BAR; PG8_MMA(0, 0, At, B0); PG8_MMA(0, 1, At, B1); PG8_BAR; PG8_SCHED;
;             PG8_LDA(At, 0, 1); PG8_STAGE(PG8_SB(0, 0), b2, voffB); PG8_STAGE(PG8_SB(0, 1), b2 + hstep, voffB); PG8_STAGE(PG8_SA(0, 0), a2, voffA);
;             PG8_WAIT_V(8); PG8_WAIT_L(0); PG8_BAR; PG8_MMA(1, 0, At, B0); PG8_MMA(1, 1, At, B1); PG8_BAR; PG8_SCHED;
	s_waitcnt lgkmcnt(0)
	v_mfma_f32_16x16x32_bf16 v[126:129], v[144:147], v[176:179], v[126:129]
	v_mfma_f32_16x16x32_bf16 v[122:125], v[152:155], v[176:179], v[122:125]
	v_mfma_f32_16x16x32_bf16 v[118:121], v[144:147], v[184:187], v[118:121]
	v_mfma_f32_16x16x32_bf16 v[110:113], v[152:155], v[184:187], v[110:113]
	v_mfma_f32_16x16x32_bf16 v[102:105], v[144:147], v[228:231], v[102:105]
	v_mfma_f32_16x16x32_bf16 v[94:97], v[152:155], v[228:231], v[94:97]
	v_mfma_f32_16x16x32_bf16 v[86:89], v[144:147], v[236:239], v[86:89]
	v_mfma_f32_16x16x32_bf16 v[78:81], v[152:155], v[236:239], v[78:81]
	v_mfma_f32_16x16x32_bf16 v[126:129], v[148:151], v[180:183], v[126:129]
	v_mfma_f32_16x16x32_bf16 v[122:125], v[156:159], v[180:183], v[122:125]
	v_mfma_f32_16x16x32_bf16 v[118:121], v[148:151], v[196:199], v[118:121]
	v_mfma_f32_16x16x32_bf16 v[110:113], v[156:159], v[196:199], v[110:113]
	v_mfma_f32_16x16x32_bf16 v[102:105], v[148:151], v[232:235], v[102:105]
	v_mfma_f32_16x16x32_bf16 v[94:97], v[156:159], v[232:235], v[94:97]
	v_mfma_f32_16x16x32_bf16 v[86:89], v[148:151], v[240:243], v[86:89]
	v_mfma_f32_16x16x32_bf16 v[78:81], v[156:159], v[240:243], v[78:81]
	v_mfma_f32_16x16x32_bf16 v[114:117], v[160:163], v[176:179], v[114:117]
	v_mfma_f32_16x16x32_bf16 v[106:109], v[168:171], v[176:179], v[106:109]
	v_mfma_f32_16x16x32_bf16 v[98:101], v[160:163], v[184:187], v[98:101]
	v_mfma_f32_16x16x32_bf16 v[90:93], v[168:171], v[184:187], v[90:93]
	v_mfma_f32_16x16x32_bf16 v[82:85], v[160:163], v[228:231], v[82:85]
	v_mfma_f32_16x16x32_bf16 v[74:77], v[168:171], v[228:231], v[74:77]
	v_mfma_f32_16x16x32_bf16 v[70:73], v[160:163], v[236:239], v[70:73]
	v_mfma_f32_16x16x32_bf16 v[66:69], v[168:171], v[236:239], v[66:69]
	v_mfma_f32_16x16x32_bf16 v[114:117], v[164:167], v[180:183], v[114:117]
	v_mfma_f32_16x16x32_bf16 v[106:109], v[172:175], v[180:183], v[106:109]
	v_mfma_f32_16x16x32_bf16 v[98:101], v[164:167], v[196:199], v[98:101]
	v_mfma_f32_16x16x32_bf16 v[90:93], v[172:175], v[196:199], v[90:93]
	v_mfma_f32_16x16x32_bf16 v[82:85], v[164:167], v[232:235], v[82:85]
	v_mfma_f32_16x16x32_bf16 v[74:77], v[172:175], v[232:235], v[74:77]
	v_mfma_f32_16x16x32_bf16 v[70:73], v[164:167], v[240:243], v[70:73]
	v_mfma_f32_16x16x32_bf16 v[66:69], v[172:175], v[240:243], v[66:69]
	s_barrier
	s_add_i32 s62, s62, s36
	v_lshl_add_u64 v[218:219], s[24:25], 0, v[0:1]
	s_mov_b32 m0, s62
	ds_read_b128 v[176:179], v143 offset:16384
	ds_read_b128 v[180:183], v143 offset:17408
	ds_read_b128 v[184:187], v143 offset:18432
	ds_read_b128 v[196:199], v143 offset:19456
	ds_read_b128 v[228:231], v143 offset:20480
	ds_read_b128 v[232:235], v143 offset:21504
	ds_read_b128 v[236:239], v143 offset:22528
	ds_read_b128 v[240:243], v143 offset:23552
	global_load_lds_dwordx4 v[218:219], off
	s_add_i32 m0, s62, 0x2000
	s_add_u32 s62, s24, 0x100000
	v_lshl_add_u64 v[244:245], s[24:25], 0, v[134:135]
	s_addc_u32 s63, s25, 0
	s_add_i32 s77, s77, s36
	global_load_lds_dwordx4 v[244:245], off
	v_lshl_add_u64 v[246:247], s[62:63], 0, v[0:1]
	s_mov_b32 m0, s77
	v_lshl_add_u64 v[248:249], s[26:27], 0, v[132:133]
	global_load_lds_dwordx4 v[246:247], off
	v_lshl_add_u64 v[246:247], s[62:63], 0, v[134:135]
	s_add_i32 m0, s77, 0x2000
	s_nop 0
	global_load_lds_dwordx4 v[246:247], off
	v_lshl_add_u64 v[246:247], s[26:27], 0, v[130:131]
	s_mov_b32 m0, s17
	s_nop 0
	global_load_lds_dwordx4 v[246:247], off
	s_mov_b32 m0, s37
	s_nop 0
	global_load_lds_dwordx4 v[248:249], off
	s_waitcnt vmcnt(8)
	s_waitcnt lgkmcnt(0)
	s_barrier
	s_waitcnt lgkmcnt(0)
	v_mfma_f32_16x16x32_bf16 v[62:65], v[144:147], v[176:179], v[62:65]
	v_mfma_f32_16x16x32_bf16 v[58:61], v[152:155], v[176:179], v[58:61]
	v_mfma_f32_16x16x32_bf16 v[54:57], v[144:147], v[184:187], v[54:57]
	v_mfma_f32_16x16x32_bf16 v[46:49], v[152:155], v[184:187], v[46:49]
	v_mfma_f32_16x16x32_bf16 v[38:41], v[144:147], v[228:231], v[38:41]
	v_mfma_f32_16x16x32_bf16 v[30:33], v[152:155], v[228:231], v[30:33]
	v_mfma_f32_16x16x32_bf16 v[22:25], v[144:147], v[236:239], v[22:25]
	v_mfma_f32_16x16x32_bf16 v[14:17], v[152:155], v[236:239], v[14:17]
	v_mfma_f32_16x16x32_bf16 v[62:65], v[148:151], v[180:183], v[62:65]
	v_mfma_f32_16x16x32_bf16 v[58:61], v[156:159], v[180:183], v[58:61]
	v_mfma_f32_16x16x32_bf16 v[54:57], v[148:151], v[196:199], v[54:57]
	v_mfma_f32_16x16x32_bf16 v[46:49], v[156:159], v[196:199], v[46:49]
	v_mfma_f32_16x16x32_bf16 v[38:41], v[148:151], v[232:235], v[38:41]
	v_mfma_f32_16x16x32_bf16 v[30:33], v[156:159], v[232:235], v[30:33]
	v_mfma_f32_16x16x32_bf16 v[22:25], v[148:151], v[240:243], v[22:25]
	v_mfma_f32_16x16x32_bf16 v[14:17], v[156:159], v[240:243], v[14:17]
	v_mfma_f32_16x16x32_bf16 v[50:53], v[160:163], v[176:179], v[50:53]
	v_mfma_f32_16x16x32_bf16 v[42:45], v[168:171], v[176:179], v[42:45]
	v_mfma_f32_16x16x32_bf16 v[34:37], v[160:163], v[184:187], v[34:37]
	v_mfma_f32_16x16x32_bf16 v[26:29], v[168:171], v[184:187], v[26:29]
	v_mfma_f32_16x16x32_bf16 v[18:21], v[160:163], v[228:231], v[18:21]
	v_mfma_f32_16x16x32_bf16 v[10:13], v[168:171], v[228:231], v[10:13]
	v_mfma_f32_16x16x32_bf16 v[6:9], v[160:163], v[236:239], v[6:9]
	v_mfma_f32_16x16x32_bf16 v[2:5], v[168:171], v[236:239], v[2:5]
	v_mfma_f32_16x16x32_bf16 v[50:53], v[164:167], v[180:183], v[50:53]
	v_mfma_f32_16x16x32_bf16 v[42:45], v[172:175], v[180:183], v[42:45]
	v_mfma_f32_16x16x32_bf16 v[34:37], v[164:167], v[196:199], v[34:37]
	v_mfma_f32_16x16x32_bf16 v[26:29], v[172:175], v[196:199], v[26:29]
	v_mfma_f32_16x16x32_bf16 v[18:21], v[164:167], v[232:235], v[18:21]
	v_mfma_f32_16x16x32_bf16 v[10:13], v[172:175], v[232:235], v[10:13]
	v_mfma_f32_16x16x32_bf16 v[6:9], v[164:167], v[240:243], v[6:9]
	v_mfma_f32_16x16x32_bf16 v[2:5], v[172:175], v[240:243], v[2:5]
	s_barrier
; #define PG8_STAGE(bufoff, gbase, voff) do { _Pragma("unroll") for (int _i = 0; _i < 2; ++_i) \
;         __builtin_amdgcn_global_load_lds((const unsigned*)((const char*)(gbase) + (voff)[_i]), (PG8_LAS unsigned*)(lds + (bufoff) + ldsw + _i * 8192), 16, 0, 0); } while (0)
; #define PG8_LDA(dst, b, h) do { _Pragma("unroll") for (int m = 0; m < 4; ++m) _Pragma("unroll") for (int k = 0; k < 2; ++k) dst[m][k] = *(const PG8_LAS bf16x8*)(lds + PG8_SA(b, h) + aoff + m * 2048 + k * 1024); } while (0)
; #define PG8_LDB(dst, b, h) do { _Pragma("unroll") for (int n = 0; n < 2; ++n) _Pragma("unroll") for (int k = 0; k < 2; ++k) dst[n][k] = *(const PG8_LAS bf16x8*)(lds + PG8_SB(b, h) + boff + n * 2048 + k * 1024); } while (0)
; #define PG8_MMA(ai, bj, At, Bt) do { __builtin_amdgcn_s_setprio(1); _Pragma("unroll") for (int m = 0; m < 4; ++m) _Pragma("unroll") for (int n = 0; n < 2; ++n) _Pragma("unroll") for (int k = 0; k < 2; ++k) \
;         acc[ai][bj][m][n] = __builtin_amdgcn_mfma_f32_16x16x32_bf16(Bt[n][k], At[m][k], acc[ai][bj][m][n], 0, 0, 0); __builtin_amdgcn_s_setprio(0); } while (0)
; #define PG8_WAIT_V(n) asm volatile("s_waitcnt vmcnt(" #n ")" ::: "memory")
; #define PG8_WAIT_L(n) asm volatile("s_waitcnt lgkmcnt(" #n ")" ::: "memory")
; #define PG8_BAR __builtin_amdgcn_s_barrier()
; #define PG8_SCHED __builtin_amdgcn_sched_barrier(0)
; template <class Epi, class Sched, bool ALIGN_EPI = false, bool SP2 = false>
; __device__ __forceinline__ void gemm_phase(PG8_LAS unsigned char* lds, const Gemm g, const Sched& S, const Epi& E, int tid_in) {
;     ...
;             PG8_LDB(B0, 1, 0); PG8_LDB(B1, 1, 1); PG8_SCHED; PG8_LDA(At, 1, 0); PG8_STAGE(PG8_SA(0, 1), a2 + hstep, voffA);
;             PG8_WAIT_V(8); PG8_WAIT_L(0); PG8_BAR; PG8_MMA(0, 0, At, B0); PG8_MMA(0, 1, At, B1); PG8_BAR; PG8_SCHED;
	s_add_i32 s62, 0, 0x18000
	s_add_i32 s63, 0, 0x1c000
	v_add_u32_e32 v156, s62, v141
	v_add_u32_e32 v172, s63, v141
	ds_read_b128 v[144:147], v156
	ds_read_b128 v[148:151], v156 offset:1024
	ds_read_b128 v[152:155], v156 offset:2048
	ds_read_b128 v[156:159], v156 offset:3072
	ds_read_b128 v[160:163], v172
	ds_read_b128 v[164:167], v172 offset:1024
	ds_read_b128 v[168:171], v172 offset:2048
	ds_read_b128 v[172:175], v172 offset:3072
	s_add_u32 s26, s26, 0x100000
	s_addc_u32 s27, s27, 0
	s_mov_b32 m0, s41
	v_lshl_add_u64 v[250:251], s[26:27], 0, v[130:131]
	ds_read_b128 v[176:179], v143 offset:32768
	ds_read_b128 v[180:183], v143 offset:33792
	ds_read_b128 v[184:187], v143 offset:34816
	ds_read_b128 v[196:199], v143 offset:35840
	ds_read_b128 v[228:231], v143 offset:36864
	ds_read_b128 v[232:235], v143 offset:37888
	ds_read_b128 v[236:239], v143 offset:38912
	ds_read_b128 v[240:243], v143 offset:39936
	global_load_lds_dwordx4 v[250:251], off
	v_lshl_add_u64 v[250:251], s[26:27], 0, v[132:133]
	s_mov_b32 m0, s46
	s_nop 0
	global_load_lds_dwordx4 v[250:251], off
	s_waitcnt vmcnt(8)
	s_waitcnt lgkmcnt(0)
	s_barrier
	s_waitcnt lgkmcnt(0)
	v_mfma_f32_16x16x32_bf16 v[126:129], v[144:147], v[176:179], v[126:129]
	v_mfma_f32_16x16x32_bf16 v[122:125], v[152:155], v[176:179], v[122:125]
	v_mfma_f32_16x16x32_bf16 v[118:121], v[144:147], v[184:187], v[118:121]
	v_mfma_f32_16x16x32_bf16 v[110:113], v[152:155], v[184:187], v[110:113]
	v_mfma_f32_16x16x32_bf16 v[102:105], v[144:147], v[228:231], v[102:105]
	v_mfma_f32_16x16x32_bf16 v[94:97], v[152:155], v[228:231], v[94:97]
	v_mfma_f32_16x16x32_bf16 v[86:89], v[144:147], v[236:239], v[86:89]
	v_mfma_f32_16x16x32_bf16 v[78:81], v[152:155], v[236:239], v[78:81]
	v_mfma_f32_16x16x32_bf16 v[126:129], v[148:151], v[180:183], v[126:129]
	v_mfma_f32_16x16x32_bf16 v[122:125], v[156:159], v[180:183], v[122:125]
	v_mfma_f32_16x16x32_bf16 v[118:121], v[148:151], v[196:199], v[118:121]
	v_mfma_f32_16x16x32_bf16 v[110:113], v[156:159], v[196:199], v[110:113]
	v_mfma_f32_16x16x32_bf16 v[102:105], v[148:151], v[232:235], v[102:105]
	v_mfma_f32_16x16x32_bf16 v[94:97], v[156:159], v[232:235], v[94:97]
	v_mfma_f32_16x16x32_bf16 v[86:89], v[148:151], v[240:243], v[86:89]
	v_mfma_f32_16x16x32_bf16 v[78:81], v[156:159], v[240:243], v[78:81]
	v_mfma_f32_16x16x32_bf16 v[114:117], v[160:163], v[176:179], v[114:117]
	v_mfma_f32_16x16x32_bf16 v[106:109], v[168:171], v[176:179], v[106:109]
	v_mfma_f32_16x16x32_bf16 v[98:101], v[160:163], v[184:187], v[98:101]
	v_mfma_f32_16x16x32_bf16 v[90:93], v[168:171], v[184:187], v[90:93]
	v_mfma_f32_16x16x32_bf16 v[82:85], v[160:163], v[228:231], v[82:85]
	v_mfma_f32_16x16x32_bf16 v[74:77], v[168:171], v[228:231], v[74:77]
	v_mfma_f32_16x16x32_bf16 v[70:73], v[160:163], v[236:239], v[70:73]
	v_mfma_f32_16x16x32_bf16 v[66:69], v[168:171], v[236:239], v[66:69]
	v_mfma_f32_16x16x32_bf16 v[114:117], v[164:167], v[180:183], v[114:117]
	v_mfma_f32_16x16x32_bf16 v[106:109], v[172:175], v[180:183], v[106:109]
	v_mfma_f32_16x16x32_bf16 v[98:101], v[164:167], v[196:199], v[98:101]
	v_mfma_f32_16x16x32_bf16 v[90:93], v[172:175], v[196:199], v[90:93]
	v_mfma_f32_16x16x32_bf16 v[82:85], v[164:167], v[232:235], v[82:85]
	v_mfma_f32_16x16x32_bf16 v[74:77], v[172:175], v[232:235], v[74:77]
	v_mfma_f32_16x16x32_bf16 v[70:73], v[164:167], v[240:243], v[70:73]
	v_mfma_f32_16x16x32_bf16 v[66:69], v[172:175], v[240:243], v[66:69]
	s_barrier
; #define PG8_STAGE(bufoff, gbase, voff) do { _Pragma("unroll") for (int _i = 0; _i < 2; ++_i) \
;         __builtin_amdgcn_global_load_lds((const unsigned*)((const char*)(gbase) + (voff)[_i]), (PG8_LAS unsigned*)(lds + (bufoff) + ldsw + _i * 8192), 16, 0, 0); } while (0)
; #define PG8_LDA(dst, b, h) do { _Pragma("unroll") for (int m = 0; m < 4; ++m) _Pragma("unroll") for (int k = 0; k < 2; ++k) dst[m][k] = *(const PG8_LAS bf16x8*)(lds + PG8_SA(b, h) + aoff + m * 2048 + k * 1024); } while (0)
; #define PG8_MMA(ai, bj, At, Bt) do { __builtin_amdgcn_s_setprio(1); _Pragma("unroll") for (int m = 0; m < 4; ++m) _Pragma("unroll") for (int n = 0; n < 2; ++n) _Pragma("unroll") for (int k = 0; k < 2; ++k) \
;         acc[ai][bj][m][n] = __builtin_amdgcn_mfma_f32_16x16x32_bf16(Bt[n][k], At[m][k], acc[ai][bj][m][n], 0, 0, 0); __builtin_amdgcn_s_setprio(0); } while (0)
; #define PG8_WAIT_V(n) asm volatile("s_waitcnt vmcnt(" #n ")" ::: "memory")
; #define PG8_WAIT_L(n) asm volatile("s_waitcnt lgkmcnt(" #n ")" ::: "memory")
; #define PG8_BAR __builtin_amdgcn_s_barrier()
; #define PG8_SCHED __builtin_amdgcn_sched_barrier(0)
; template <class Epi, class Sched, bool ALIGN_EPI = false, bool SP2 = false>
; __device__ __forceinline__ void gemm_phase(PG8_LAS unsigned char* lds, const Gemm g, const Sched& S, const Epi& E, int tid_in) {
;     ...
;             PG8_LDA(At, 1, 1); PG8_STAGE(PG8_SB(1, 0), b3, voffB); PG8_STAGE(PG8_SB(1, 1), b3 + hstep, voffB); PG8_STAGE(PG8_SA(1, 0), a3, voffA);
;             PG8_WAIT_V(8); PG8_WAIT_L(0); PG8_BAR; PG8_MMA(1, 0, At, B0); PG8_MMA(1, 1, At, B1); PG8_BAR; PG8_SCHED;
;     ...
;         }
;         if constexpr (ALIGN_EPI) { if (wr == 0) PG8_BAR; }
	s_add_i32 s26, s62, s36
	v_lshl_add_u64 v[218:219], v[218:219], 0, s[54:55]
	s_mov_b32 m0, s26
	ds_read_b128 v[176:179], v143 offset:49152
	ds_read_b128 v[180:183], v143 offset:50176
	ds_read_b128 v[184:187], v143 offset:51200
	ds_read_b128 v[196:199], v143 offset:52224
	ds_read_b128 v[228:231], v143 offset:53248
	ds_read_b128 v[232:235], v143 offset:54272
	ds_read_b128 v[236:239], v143 offset:55296
	ds_read_b128 v[240:243], v143 offset:56320
	global_load_lds_dwordx4 v[218:219], off
	s_add_i32 m0, s26, 0x2000
	s_add_u32 s24, s24, 0x100080
	v_lshl_add_u64 v[218:219], v[244:245], 0, s[54:55]
	s_addc_u32 s25, s25, 0
	s_add_i32 s26, s63, s36
	global_load_lds_dwordx4 v[218:219], off
	v_lshl_add_u64 v[218:219], s[24:25], 0, v[0:1]
	s_mov_b32 m0, s26
	s_nop 0
	global_load_lds_dwordx4 v[218:219], off
	v_lshl_add_u64 v[218:219], s[24:25], 0, v[134:135]
	s_add_i32 m0, s26, 0x2000
	s_nop 0
	global_load_lds_dwordx4 v[218:219], off
	v_lshl_add_u64 v[218:219], v[246:247], 0, s[54:55]
	s_mov_b32 m0, s47
	s_nop 0
	global_load_lds_dwordx4 v[218:219], off
	v_lshl_add_u64 v[218:219], v[248:249], 0, s[54:55]
	s_mov_b32 m0, s48
	s_nop 0
	global_load_lds_dwordx4 v[218:219], off
	s_waitcnt vmcnt(8)
	s_waitcnt lgkmcnt(0)
	s_barrier
	s_waitcnt lgkmcnt(0)
	v_mfma_f32_16x16x32_bf16 v[62:65], v[144:147], v[176:179], v[62:65]
	v_mfma_f32_16x16x32_bf16 v[58:61], v[152:155], v[176:179], v[58:61]
	v_mfma_f32_16x16x32_bf16 v[54:57], v[144:147], v[184:187], v[54:57]
	v_mfma_f32_16x16x32_bf16 v[46:49], v[152:155], v[184:187], v[46:49]
	v_mfma_f32_16x16x32_bf16 v[38:41], v[144:147], v[228:231], v[38:41]
	v_mfma_f32_16x16x32_bf16 v[30:33], v[152:155], v[228:231], v[30:33]
	v_mfma_f32_16x16x32_bf16 v[22:25], v[144:147], v[236:239], v[22:25]
	v_mfma_f32_16x16x32_bf16 v[14:17], v[152:155], v[236:239], v[14:17]
	v_mfma_f32_16x16x32_bf16 v[62:65], v[148:151], v[180:183], v[62:65]
	v_mfma_f32_16x16x32_bf16 v[58:61], v[156:159], v[180:183], v[58:61]
	v_mfma_f32_16x16x32_bf16 v[54:57], v[148:151], v[196:199], v[54:57]
	v_mfma_f32_16x16x32_bf16 v[46:49], v[156:159], v[196:199], v[46:49]
	v_mfma_f32_16x16x32_bf16 v[38:41], v[148:151], v[232:235], v[38:41]
	v_mfma_f32_16x16x32_bf16 v[30:33], v[156:159], v[232:235], v[30:33]
	v_mfma_f32_16x16x32_bf16 v[22:25], v[148:151], v[240:243], v[22:25]
	v_mfma_f32_16x16x32_bf16 v[14:17], v[156:159], v[240:243], v[14:17]
	v_mfma_f32_16x16x32_bf16 v[50:53], v[160:163], v[176:179], v[50:53]
	v_mfma_f32_16x16x32_bf16 v[42:45], v[168:171], v[176:179], v[42:45]
	v_mfma_f32_16x16x32_bf16 v[34:37], v[160:163], v[184:187], v[34:37]
	v_mfma_f32_16x16x32_bf16 v[26:29], v[168:171], v[184:187], v[26:29]
	v_mfma_f32_16x16x32_bf16 v[18:21], v[160:163], v[228:231], v[18:21]
	v_mfma_f32_16x16x32_bf16 v[10:13], v[168:171], v[228:231], v[10:13]
	v_mfma_f32_16x16x32_bf16 v[6:9], v[160:163], v[236:239], v[6:9]
	v_mfma_f32_16x16x32_bf16 v[2:5], v[168:171], v[236:239], v[2:5]
	v_mfma_f32_16x16x32_bf16 v[50:53], v[164:167], v[180:183], v[50:53]
	v_mfma_f32_16x16x32_bf16 v[42:45], v[172:175], v[180:183], v[42:45]
	v_mfma_f32_16x16x32_bf16 v[34:37], v[164:167], v[196:199], v[34:37]
	v_mfma_f32_16x16x32_bf16 v[26:29], v[172:175], v[196:199], v[26:29]
	v_mfma_f32_16x16x32_bf16 v[18:21], v[164:167], v[232:235], v[18:21]
	v_mfma_f32_16x16x32_bf16 v[10:13], v[172:175], v[232:235], v[10:13]
	v_mfma_f32_16x16x32_bf16 v[6:9], v[164:167], v[240:243], v[6:9]
	v_mfma_f32_16x16x32_bf16 v[2:5], v[172:175], v[240:243], v[2:5]
	s_barrier
	s_add_i32 s76, s76, 2
	s_add_u32 s22, s22, 0x100
	s_addc_u32 s23, s23, 0
	s_add_u32 s74, s74, 0x100
	s_addc_u32 s75, s75, 0
	s_cmp_gt_u32 s76, 61
	s_cbranch_scc0 .LBB0_755
	s_setprio 0
	s_and_b64 vcc, exec, s[10:11]
	s_cbranch_vccz .LBB0_758
	s_barrier

; #define PG8_STAGE(bufoff, gbase, voff) do { _Pragma("unroll") for (int _i = 0; _i < 2; ++_i) \
;         __builtin_amdgcn_global_load_lds((const unsigned*)((const char*)(gbase) + (voff)[_i]), (PG8_LAS unsigned*)(lds + (bufoff) + ldsw + _i * 8192), 16, 0, 0); } while (0)
; #define PG8_LDA(dst, b, h) do { _Pragma("unroll") for (int m = 0; m < 4; ++m) _Pragma("unroll") for (int k = 0; k < 2; ++k) dst[m][k] = *(const PG8_LAS bf16x8*)(lds + PG8_SA(b, h) + aoff + m * 2048 + k * 1024); } while (0)
; #define PG8_LDB(dst, b, h) do { _Pragma("unroll") for (int n = 0; n < 2; ++n) _Pragma("unroll") for (int k = 0; k < 2; ++k) dst[n][k] = *(const PG8_LAS bf16x8*)(lds + PG8_SB(b, h) + boff + n * 2048 + k * 1024); } while (0)
; #define PG8_SCHED __builtin_amdgcn_sched_barrier(0)
;   __device__ __forceinline__ bool next(int i,AttnUnit&u)const{ if(i>=2)return false; const int s=vcu&15; u.bh=vcu>>4; u.qb=(i==0)?31-s:s; return true; }
; template <class Epi, class Sched, bool ALIGN_EPI = false, bool SP2 = false>
; __device__ __forceinline__ void gemm_phase(PG8_LAS unsigned char* lds, const Gemm g, const Sched& S, const Epi& E, int tid_in) {
;     ...
;         const bool has_next = S.next(ui + 1, nxt);
;         const char* nA = has_next ? (const char*)g.A + (size_t)nxt.pm * tstep : cA; const char* nB = has_next ? (const char*)g.Bt + (size_t)nxt.pn * tstep : cB;
;         for (int t = 0; t < nt; t += 2) {
;             const bool last = (t == nt - 2);
;             const char* a1 = cA + (size_t)(t + 1) * kstep;
;             const char* a2 = last ? nA : cA + (size_t)(t + 2) * kstep; const char* b2 = last ? nB : cB + (size_t)(t + 2) * kstep;
;             const char* a3 = a2 + kstep; const char* b3 = b2 + kstep;
;             if (last && has_next) S.a_ready(nxt);
;             if constexpr (SP2) {
;             PG8_LDB(B0, 0, 0); PG8_LDB(B1, 0, 1); PG8_SCHED; PG8_LDA(At, 0, 0); PG8_STAGE(PG8_SA(1, 1), a1 + hstep, voffA);
;     ...
; #pragma unroll
;         for (int a = 0; a < 2; ++a)
; #pragma unroll
;             for (int b = 0; b < 2; ++b)
; #pragma unroll
;                 for (int m = 0; m < 4; ++m)
; #pragma unroll
;                     for (int n = 0; n < 2; ++n) acc[a][b][m][n] = (f32x4){0.f, 0.f, 0.f, 0.f};
;         cur = nxt; cA = nA; cB = nB; ++ui;
.LBB0_919:
	s_ashr_i32 s19, s18, 31
	s_lshl_b64 s[20:21], s[18:19], 19
	s_add_u32 s20, s37, s20
	s_addc_u32 s21, s70, s21
	s_and_b64 s[22:23], s[4:5], exec
	s_cselect_b32 s19, s21, s27
	s_cselect_b32 s25, s20, s26
	s_ashr_i32 s17, s16, 31
	s_lshl_b64 s[22:23], s[16:17], 19
	s_add_u32 s22, s71, s22
	s_addc_u32 s23, s72, s23
	s_and_b64 s[30:31], s[4:5], exec
	s_cselect_b32 s17, s23, s29
	s_cselect_b32 s41, s22, s28
	s_add_u32 s26, s26, 0x40080
	s_addc_u32 s27, s27, 0
	s_add_u32 s46, s28, 0x100
	v_mov_b32_e32 v2, 0
	s_addc_u32 s47, s29, 0
	s_mov_b32 s48, -2
	v_mov_b32_e32 v3, v2
	v_mov_b32_e32 v4, v2
	v_mov_b32_e32 v5, v2
	v_mov_b32_e32 v6, v2
	v_mov_b32_e32 v7, v2
	v_mov_b32_e32 v8, v2
	v_mov_b32_e32 v9, v2
	v_mov_b32_e32 v18, v2
	v_mov_b32_e32 v19, v2
	v_mov_b32_e32 v20, v2
	v_mov_b32_e32 v21, v2
	v_mov_b32_e32 v22, v2
	v_mov_b32_e32 v23, v2
	v_mov_b32_e32 v24, v2
	v_mov_b32_e32 v25, v2
	v_mov_b32_e32 v34, v2
	v_mov_b32_e32 v35, v2
	v_mov_b32_e32 v36, v2
	v_mov_b32_e32 v37, v2
	v_mov_b32_e32 v38, v2
	v_mov_b32_e32 v39, v2
	v_mov_b32_e32 v40, v2
	v_mov_b32_e32 v41, v2
	v_mov_b32_e32 v50, v2
	v_mov_b32_e32 v51, v2
	v_mov_b32_e32 v52, v2
	v_mov_b32_e32 v53, v2
	v_mov_b32_e32 v54, v2
	v_mov_b32_e32 v55, v2
	v_mov_b32_e32 v56, v2
	v_mov_b32_e32 v57, v2
	v_mov_b32_e32 v10, v2
	v_mov_b32_e32 v11, v2
	v_mov_b32_e32 v12, v2
	v_mov_b32_e32 v13, v2
	v_mov_b32_e32 v14, v2
	v_mov_b32_e32 v15, v2
	v_mov_b32_e32 v16, v2
	v_mov_b32_e32 v17, v2
	v_mov_b32_e32 v26, v2
	v_mov_b32_e32 v27, v2
	v_mov_b32_e32 v28, v2
	v_mov_b32_e32 v29, v2
	v_mov_b32_e32 v30, v2
	v_mov_b32_e32 v31, v2
	v_mov_b32_e32 v32, v2
	v_mov_b32_e32 v33, v2
	v_mov_b32_e32 v42, v2
	v_mov_b32_e32 v43, v2
	v_mov_b32_e32 v44, v2
	v_mov_b32_e32 v45, v2
	v_mov_b32_e32 v46, v2
	v_mov_b32_e32 v47, v2
	v_mov_b32_e32 v48, v2
	v_mov_b32_e32 v49, v2
	v_mov_b32_e32 v58, v2
	v_mov_b32_e32 v59, v2
	v_mov_b32_e32 v60, v2
	v_mov_b32_e32 v61, v2
	v_mov_b32_e32 v62, v2
	v_mov_b32_e32 v63, v2
	v_mov_b32_e32 v64, v2
	v_mov_b32_e32 v65, v2
	v_mov_b32_e32 v66, v2
	v_mov_b32_e32 v67, v2
	v_mov_b32_e32 v68, v2
	v_mov_b32_e32 v69, v2
	v_mov_b32_e32 v70, v2
	v_mov_b32_e32 v71, v2
	v_mov_b32_e32 v72, v2
	v_mov_b32_e32 v73, v2
	v_mov_b32_e32 v82, v2
	v_mov_b32_e32 v83, v2
	v_mov_b32_e32 v84, v2
	v_mov_b32_e32 v85, v2
	v_mov_b32_e32 v86, v2
	v_mov_b32_e32 v87, v2
	v_mov_b32_e32 v88, v2
	v_mov_b32_e32 v89, v2
	v_mov_b32_e32 v98, v2
	v_mov_b32_e32 v99, v2
	v_mov_b32_e32 v100, v2
	v_mov_b32_e32 v101, v2
	v_mov_b32_e32 v102, v2
	v_mov_b32_e32 v103, v2
	v_mov_b32_e32 v104, v2
	v_mov_b32_e32 v105, v2
	v_mov_b32_e32 v114, v2
	v_mov_b32_e32 v115, v2
	v_mov_b32_e32 v116, v2
	v_mov_b32_e32 v117, v2
	v_mov_b32_e32 v118, v2
	v_mov_b32_e32 v119, v2
	v_mov_b32_e32 v120, v2
	v_mov_b32_e32 v121, v2
	v_mov_b32_e32 v74, v2
	v_mov_b32_e32 v75, v2
	v_mov_b32_e32 v76, v2
	v_mov_b32_e32 v77, v2
	v_mov_b32_e32 v78, v2
	v_mov_b32_e32 v79, v2
	v_mov_b32_e32 v80, v2
	v_mov_b32_e32 v81, v2
	v_mov_b32_e32 v90, v2
	v_mov_b32_e32 v91, v2
	v_mov_b32_e32 v92, v2
	v_mov_b32_e32 v93, v2
	v_mov_b32_e32 v94, v2
	v_mov_b32_e32 v95, v2
	v_mov_b32_e32 v96, v2
	v_mov_b32_e32 v97, v2
	v_mov_b32_e32 v106, v2
	v_mov_b32_e32 v107, v2
	v_mov_b32_e32 v108, v2
	v_mov_b32_e32 v109, v2
	v_mov_b32_e32 v110, v2
	v_mov_b32_e32 v111, v2
	v_mov_b32_e32 v112, v2
	v_mov_b32_e32 v113, v2
	v_mov_b32_e32 v122, v2
	v_mov_b32_e32 v123, v2
	v_mov_b32_e32 v124, v2
	v_mov_b32_e32 v125, v2
	v_mov_b32_e32 v126, v2
	v_mov_b32_e32 v127, v2
	v_mov_b32_e32 v128, v2
	v_mov_b32_e32 v129, v2
	s_and_b64 s[98:99], exec, s[14:15]
	s_cbranch_scc0 .Lprio_skip_920
	s_setprio 1
.Lprio_skip_920:
.LBB0_920:
	s_add_u32 s28, s26, 0xfffc0080
	s_addc_u32 s29, s27, -1
	s_add_i32 s49, 0, 0x10000
	s_cmp_eq_u32 s48, 12
	s_cselect_b32 s31, s19, s29
	s_cselect_b32 s30, s25, s28
	v_add_u32_e32 v144, s49, v150
	s_cselect_b32 s29, s17, s47
	s_cselect_b32 s28, s41, s46
	s_add_i32 s52, 0, 0x14000
	ds_read_b128 v[140:143], v144
	ds_read_b128 v[154:157], v144 offset:1024
	ds_read_b128 v[158:161], v144 offset:2048
	ds_read_b128 v[162:165], v144 offset:3072
	v_add_u32_e32 v144, s52, v150
	ds_read_b128 v[166:169], v144
	ds_read_b128 v[170:173], v144 offset:1024
	ds_read_b128 v[174:177], v144 offset:2048
	ds_read_b128 v[178:181], v144 offset:3072
	v_lshl_add_u64 v[144:145], s[26:27], 0, v[136:137]
	s_add_i32 m0, s74, 0xc000
	ds_read_b128 v[182:185], v152
	ds_read_b128 v[196:199], v152 offset:1024
	ds_read_b128 v[228:231], v152 offset:2048
	ds_read_b128 v[232:235], v152 offset:3072
	ds_read_b128 v[236:239], v152 offset:4096
	ds_read_b128 v[240:243], v152 offset:5120
	ds_read_b128 v[244:247], v152 offset:6144
	ds_read_b128 v[248:251], v152 offset:7168
	global_load_lds_dwordx4 v[144:145], off
	v_lshl_add_u64 v[144:145], s[26:27], 0, v[138:139]
	s_add_i32 m0, s74, 0xe000
	s_nop 0
	global_load_lds_dwordx4 v[144:145], off
	s_waitcnt vmcnt(8)
	s_waitcnt lgkmcnt(0)
	s_barrier
; #define PG8_STAGE(bufoff, gbase, voff) do { _Pragma("unroll") for (int _i = 0; _i < 2; ++_i) \
;         __builtin_amdgcn_global_load_lds((const unsigned*)((const char*)(gbase) + (voff)[_i]), (PG8_LAS unsigned*)(lds + (bufoff) + ldsw + _i * 8192), 16, 0, 0); } while (0)
; #define PG8_LDA(dst, b, h) do { _Pragma("unroll") for (int m = 0; m < 4; ++m) _Pragma("unroll") for (int k = 0; k < 2; ++k) dst[m][k] = *(const PG8_LAS bf16x8*)(lds + PG8_SA(b, h) + aoff + m * 2048 + k * 1024); } while (0)
; #define PG8_MMA(ai, bj, At, Bt) do { __builtin_amdgcn_s_setprio(1); _Pragma("unroll") for (int m = 0; m < 4; ++m) _Pragma("unroll") for (int n = 0; n < 2; ++n) _Pragma("unroll") for (int k = 0; k < 2; ++k) \
;         acc[ai][bj][m][n] = __builtin_amdgcn_mfma_f32_16x16x32_bf16(Bt[n][k], At[m][k], acc[ai][bj][m][n], 0, 0, 0); __builtin_amdgcn_s_setprio(0); } while (0)
; #define PG8_WAIT_V(n) asm volatile("s_waitcnt vmcnt(" #n ")" ::: "memory")
; #define PG8_WAIT_L(n) asm volatile("s_waitcnt lgkmcnt(" #n ")" ::: "memory")
; #define PG8_BAR __builtin_amdgcn_s_barrier()
; #define PG8_SCHED __builtin_amdgcn_sched_barrier(0)
; template <class Epi, class Sched, bool ALIGN_EPI = false, bool SP2 = false>
; __device__ __forceinline__ void gemm_phase(PG8_LAS unsigned char* lds, const Gemm g, const Sched& S, const Epi& E, int tid_in) {
;     ...
;             PG8_WAIT_V(8); PG8_WAIT_L(0); PG8_BAR; PG8_MMA(0, 0, At, B0); PG8_MMA(0, 1, At, B1); PG8_BAR; PG8_SCHED;
;             PG8_LDA(At, 0, 1); PG8_STAGE(PG8_SB(0, 0), b2, voffB); PG8_STAGE(PG8_SB(0, 1), b2 + hstep, voffB); PG8_STAGE(PG8_SA(0, 0), a2, voffA);
;             PG8_WAIT_V(8); PG8_WAIT_L(0); PG8_BAR; PG8_MMA(1, 0, At, B0); PG8_MMA(1, 1, At, B1); PG8_BAR; PG8_SCHED;
	s_waitcnt lgkmcnt(0)
	v_mfma_f32_16x16x32_bf16 v[126:129], v[140:143], v[182:185], v[126:129]
	v_mfma_f32_16x16x32_bf16 v[122:125], v[158:161], v[182:185], v[122:125]
	v_mfma_f32_16x16x32_bf16 v[110:113], v[140:143], v[228:231], v[110:113]
	v_mfma_f32_16x16x32_bf16 v[106:109], v[158:161], v[228:231], v[106:109]
	v_mfma_f32_16x16x32_bf16 v[94:97], v[140:143], v[236:239], v[94:97]
	v_mfma_f32_16x16x32_bf16 v[90:93], v[158:161], v[236:239], v[90:93]
	v_mfma_f32_16x16x32_bf16 v[78:81], v[140:143], v[244:247], v[78:81]
	v_mfma_f32_16x16x32_bf16 v[74:77], v[158:161], v[244:247], v[74:77]
	v_mfma_f32_16x16x32_bf16 v[126:129], v[154:157], v[196:199], v[126:129]
	v_mfma_f32_16x16x32_bf16 v[122:125], v[162:165], v[196:199], v[122:125]
	v_mfma_f32_16x16x32_bf16 v[110:113], v[154:157], v[232:235], v[110:113]
	v_mfma_f32_16x16x32_bf16 v[106:109], v[162:165], v[232:235], v[106:109]
	v_mfma_f32_16x16x32_bf16 v[94:97], v[154:157], v[240:243], v[94:97]
	v_mfma_f32_16x16x32_bf16 v[90:93], v[162:165], v[240:243], v[90:93]
	v_mfma_f32_16x16x32_bf16 v[78:81], v[154:157], v[248:251], v[78:81]
	v_mfma_f32_16x16x32_bf16 v[74:77], v[162:165], v[248:251], v[74:77]
	v_mfma_f32_16x16x32_bf16 v[118:121], v[166:169], v[182:185], v[118:121]
	v_mfma_f32_16x16x32_bf16 v[114:117], v[174:177], v[182:185], v[114:117]
	v_mfma_f32_16x16x32_bf16 v[102:105], v[166:169], v[228:231], v[102:105]
	v_mfma_f32_16x16x32_bf16 v[98:101], v[174:177], v[228:231], v[98:101]
	v_mfma_f32_16x16x32_bf16 v[86:89], v[166:169], v[236:239], v[86:89]
	v_mfma_f32_16x16x32_bf16 v[82:85], v[174:177], v[236:239], v[82:85]
	v_mfma_f32_16x16x32_bf16 v[70:73], v[166:169], v[244:247], v[70:73]
	v_mfma_f32_16x16x32_bf16 v[66:69], v[174:177], v[244:247], v[66:69]
	v_mfma_f32_16x16x32_bf16 v[118:121], v[170:173], v[196:199], v[118:121]
	v_mfma_f32_16x16x32_bf16 v[114:117], v[178:181], v[196:199], v[114:117]
	v_mfma_f32_16x16x32_bf16 v[102:105], v[170:173], v[232:235], v[102:105]
	v_mfma_f32_16x16x32_bf16 v[98:101], v[178:181], v[232:235], v[98:101]
	v_mfma_f32_16x16x32_bf16 v[86:89], v[170:173], v[240:243], v[86:89]
	v_mfma_f32_16x16x32_bf16 v[82:85], v[178:181], v[240:243], v[82:85]
	v_mfma_f32_16x16x32_bf16 v[70:73], v[170:173], v[248:251], v[70:73]
	v_mfma_f32_16x16x32_bf16 v[66:69], v[178:181], v[248:251], v[66:69]
	s_barrier
	s_add_i32 s49, s49, s73
	v_lshl_add_u64 v[144:145], s[28:29], 0, v[0:1]
	s_mov_b32 m0, s49
	ds_read_b128 v[182:185], v152 offset:16384
	ds_read_b128 v[196:199], v152 offset:17408
	ds_read_b128 v[228:231], v152 offset:18432
	ds_read_b128 v[232:235], v152 offset:19456
	ds_read_b128 v[236:239], v152 offset:20480
	ds_read_b128 v[240:243], v152 offset:21504
	ds_read_b128 v[244:247], v152 offset:22528
	ds_read_b128 v[248:251], v152 offset:23552
	global_load_lds_dwordx4 v[144:145], off
	s_add_i32 m0, s49, 0x2000
	s_add_u32 s62, s28, 0x40000
	v_lshl_add_u64 v[148:149], s[28:29], 0, v[134:135]
	s_addc_u32 s63, s29, 0
	s_add_i32 s49, s52, s73
	global_load_lds_dwordx4 v[148:149], off
	v_lshl_add_u64 v[186:187], s[62:63], 0, v[0:1]
	s_mov_b32 m0, s49
	v_lshl_add_u64 v[218:219], s[30:31], 0, v[132:133]
	global_load_lds_dwordx4 v[186:187], off
	v_lshl_add_u64 v[186:187], s[62:63], 0, v[134:135]
	s_add_i32 m0, s49, 0x2000
	s_nop 0
	global_load_lds_dwordx4 v[186:187], off
	v_lshl_add_u64 v[186:187], s[30:31], 0, v[130:131]
	s_mov_b32 m0, s74
	s_nop 0
	global_load_lds_dwordx4 v[186:187], off
	s_mov_b32 m0, s75
	s_nop 0
	global_load_lds_dwordx4 v[218:219], off
	s_waitcnt vmcnt(8)
	s_waitcnt lgkmcnt(0)
	s_barrier
	s_waitcnt lgkmcnt(0)
	v_mfma_f32_16x16x32_bf16 v[62:65], v[140:143], v[182:185], v[62:65]
	v_mfma_f32_16x16x32_bf16 v[58:61], v[158:161], v[182:185], v[58:61]
	v_mfma_f32_16x16x32_bf16 v[46:49], v[140:143], v[228:231], v[46:49]
	v_mfma_f32_16x16x32_bf16 v[42:45], v[158:161], v[228:231], v[42:45]
	v_mfma_f32_16x16x32_bf16 v[30:33], v[140:143], v[236:239], v[30:33]
	v_mfma_f32_16x16x32_bf16 v[26:29], v[158:161], v[236:239], v[26:29]
	v_mfma_f32_16x16x32_bf16 v[14:17], v[140:143], v[244:247], v[14:17]
	v_mfma_f32_16x16x32_bf16 v[10:13], v[158:161], v[244:247], v[10:13]
	v_mfma_f32_16x16x32_bf16 v[62:65], v[154:157], v[196:199], v[62:65]
	v_mfma_f32_16x16x32_bf16 v[58:61], v[162:165], v[196:199], v[58:61]
	v_mfma_f32_16x16x32_bf16 v[46:49], v[154:157], v[232:235], v[46:49]
	v_mfma_f32_16x16x32_bf16 v[42:45], v[162:165], v[232:235], v[42:45]
	v_mfma_f32_16x16x32_bf16 v[30:33], v[154:157], v[240:243], v[30:33]
	v_mfma_f32_16x16x32_bf16 v[26:29], v[162:165], v[240:243], v[26:29]
	v_mfma_f32_16x16x32_bf16 v[14:17], v[154:157], v[248:251], v[14:17]
	v_mfma_f32_16x16x32_bf16 v[10:13], v[162:165], v[248:251], v[10:13]
	v_mfma_f32_16x16x32_bf16 v[54:57], v[166:169], v[182:185], v[54:57]
	v_mfma_f32_16x16x32_bf16 v[50:53], v[174:177], v[182:185], v[50:53]
	v_mfma_f32_16x16x32_bf16 v[38:41], v[166:169], v[228:231], v[38:41]
	v_mfma_f32_16x16x32_bf16 v[34:37], v[174:177], v[228:231], v[34:37]
	v_mfma_f32_16x16x32_bf16 v[22:25], v[166:169], v[236:239], v[22:25]
	v_mfma_f32_16x16x32_bf16 v[18:21], v[174:177], v[236:239], v[18:21]
	v_mfma_f32_16x16x32_bf16 v[6:9], v[166:169], v[244:247], v[6:9]
	v_mfma_f32_16x16x32_bf16 v[2:5], v[174:177], v[244:247], v[2:5]
	v_mfma_f32_16x16x32_bf16 v[54:57], v[170:173], v[196:199], v[54:57]
	v_mfma_f32_16x16x32_bf16 v[50:53], v[178:181], v[196:199], v[50:53]
	v_mfma_f32_16x16x32_bf16 v[38:41], v[170:173], v[232:235], v[38:41]
	v_mfma_f32_16x16x32_bf16 v[34:37], v[178:181], v[232:235], v[34:37]
	v_mfma_f32_16x16x32_bf16 v[22:25], v[170:173], v[240:243], v[22:25]
	v_mfma_f32_16x16x32_bf16 v[18:21], v[178:181], v[240:243], v[18:21]
	v_mfma_f32_16x16x32_bf16 v[6:9], v[170:173], v[248:251], v[6:9]
	v_mfma_f32_16x16x32_bf16 v[2:5], v[178:181], v[248:251], v[2:5]
	s_barrier
; #define PG8_STAGE(bufoff, gbase, voff) do { _Pragma("unroll") for (int _i = 0; _i < 2; ++_i) \
;         __builtin_amdgcn_global_load_lds((const unsigned*)((const char*)(gbase) + (voff)[_i]), (PG8_LAS unsigned*)(lds + (bufoff) + ldsw + _i * 8192), 16, 0, 0); } while (0)
; #define PG8_LDA(dst, b, h) do { _Pragma("unroll") for (int m = 0; m < 4; ++m) _Pragma("unroll") for (int k = 0; k < 2; ++k) dst[m][k] = *(const PG8_LAS bf16x8*)(lds + PG8_SA(b, h) + aoff + m * 2048 + k * 1024); } while (0)
; #define PG8_LDB(dst, b, h) do { _Pragma("unroll") for (int n = 0; n < 2; ++n) _Pragma("unroll") for (int k = 0; k < 2; ++k) dst[n][k] = *(const PG8_LAS bf16x8*)(lds + PG8_SB(b, h) + boff + n * 2048 + k * 1024); } while (0)
; #define PG8_MMA(ai, bj, At, Bt) do { __builtin_amdgcn_s_setprio(1); _Pragma("unroll") for (int m = 0; m < 4; ++m) _Pragma("unroll") for (int n = 0; n < 2; ++n) _Pragma("unroll") for (int k = 0; k < 2; ++k) \
;         acc[ai][bj][m][n] = __builtin_amdgcn_mfma_f32_16x16x32_bf16(Bt[n][k], At[m][k], acc[ai][bj][m][n], 0, 0, 0); __builtin_amdgcn_s_setprio(0); } while (0)
; #define PG8_WAIT_V(n) asm volatile("s_waitcnt vmcnt(" #n ")" ::: "memory")
; #define PG8_WAIT_L(n) asm volatile("s_waitcnt lgkmcnt(" #n ")" ::: "memory")
; #define PG8_BAR __builtin_amdgcn_s_barrier()
; #define PG8_SCHED __builtin_amdgcn_sched_barrier(0)
; template <class Epi, class Sched, bool ALIGN_EPI = false, bool SP2 = false>
; __device__ __forceinline__ void gemm_phase(PG8_LAS unsigned char* lds, const Gemm g, const Sched& S, const Epi& E, int tid_in) {
;     ...
;             PG8_LDB(B0, 1, 0); PG8_LDB(B1, 1, 1); PG8_SCHED; PG8_LDA(At, 1, 0); PG8_STAGE(PG8_SA(0, 1), a2 + hstep, voffA);
;             PG8_WAIT_V(8); PG8_WAIT_L(0); PG8_BAR; PG8_MMA(0, 0, At, B0); PG8_MMA(0, 1, At, B1); PG8_BAR; PG8_SCHED;
	s_add_i32 s49, 0, 0x18000
	v_add_u32_e32 v146, s49, v150
	s_add_i32 s52, 0, 0x1c000
	ds_read_b128 v[140:143], v146
	ds_read_b128 v[154:157], v146 offset:1024
	ds_read_b128 v[158:161], v146 offset:2048
	ds_read_b128 v[162:165], v146 offset:3072
	v_add_u32_e32 v146, s52, v150
	ds_read_b128 v[166:169], v146
	ds_read_b128 v[170:173], v146 offset:1024
	ds_read_b128 v[174:177], v146 offset:2048
	ds_read_b128 v[178:181], v146 offset:3072
	s_add_u32 s30, s30, 0x40000
	s_addc_u32 s31, s31, 0
	s_mov_b32 m0, s76
	v_lshl_add_u64 v[252:253], s[30:31], 0, v[130:131]
	ds_read_b128 v[182:185], v152 offset:32768
	ds_read_b128 v[196:199], v152 offset:33792
	ds_read_b128 v[228:231], v152 offset:34816
	ds_read_b128 v[232:235], v152 offset:35840
	ds_read_b128 v[236:239], v152 offset:36864
	ds_read_b128 v[240:243], v152 offset:37888
	ds_read_b128 v[244:247], v152 offset:38912
	ds_read_b128 v[248:251], v152 offset:39936
	global_load_lds_dwordx4 v[252:253], off
	v_lshl_add_u64 v[252:253], s[30:31], 0, v[132:133]
	s_mov_b32 m0, s77
	s_nop 0
	global_load_lds_dwordx4 v[252:253], off
	s_waitcnt vmcnt(8)
	s_waitcnt lgkmcnt(0)
	s_barrier
	s_waitcnt lgkmcnt(0)
	v_mfma_f32_16x16x32_bf16 v[126:129], v[140:143], v[182:185], v[126:129]
	v_mfma_f32_16x16x32_bf16 v[122:125], v[158:161], v[182:185], v[122:125]
	v_mfma_f32_16x16x32_bf16 v[110:113], v[140:143], v[228:231], v[110:113]
	v_mfma_f32_16x16x32_bf16 v[106:109], v[158:161], v[228:231], v[106:109]
	v_mfma_f32_16x16x32_bf16 v[94:97], v[140:143], v[236:239], v[94:97]
	v_mfma_f32_16x16x32_bf16 v[90:93], v[158:161], v[236:239], v[90:93]
	v_mfma_f32_16x16x32_bf16 v[78:81], v[140:143], v[244:247], v[78:81]
	v_mfma_f32_16x16x32_bf16 v[74:77], v[158:161], v[244:247], v[74:77]
	v_mfma_f32_16x16x32_bf16 v[126:129], v[154:157], v[196:199], v[126:129]
	v_mfma_f32_16x16x32_bf16 v[122:125], v[162:165], v[196:199], v[122:125]
	v_mfma_f32_16x16x32_bf16 v[110:113], v[154:157], v[232:235], v[110:113]
	v_mfma_f32_16x16x32_bf16 v[106:109], v[162:165], v[232:235], v[106:109]
	v_mfma_f32_16x16x32_bf16 v[94:97], v[154:157], v[240:243], v[94:97]
	v_mfma_f32_16x16x32_bf16 v[90:93], v[162:165], v[240:243], v[90:93]
	v_mfma_f32_16x16x32_bf16 v[78:81], v[154:157], v[248:251], v[78:81]
	v_mfma_f32_16x16x32_bf16 v[74:77], v[162:165], v[248:251], v[74:77]
	v_mfma_f32_16x16x32_bf16 v[118:121], v[166:169], v[182:185], v[118:121]
	v_mfma_f32_16x16x32_bf16 v[114:117], v[174:177], v[182:185], v[114:117]
	v_mfma_f32_16x16x32_bf16 v[102:105], v[166:169], v[228:231], v[102:105]
	v_mfma_f32_16x16x32_bf16 v[98:101], v[174:177], v[228:231], v[98:101]
	v_mfma_f32_16x16x32_bf16 v[86:89], v[166:169], v[236:239], v[86:89]
	v_mfma_f32_16x16x32_bf16 v[82:85], v[174:177], v[236:239], v[82:85]
	v_mfma_f32_16x16x32_bf16 v[70:73], v[166:169], v[244:247], v[70:73]
	v_mfma_f32_16x16x32_bf16 v[66:69], v[174:177], v[244:247], v[66:69]
	v_mfma_f32_16x16x32_bf16 v[118:121], v[170:173], v[196:199], v[118:121]
	v_mfma_f32_16x16x32_bf16 v[114:117], v[178:181], v[196:199], v[114:117]
	v_mfma_f32_16x16x32_bf16 v[102:105], v[170:173], v[232:235], v[102:105]
	v_mfma_f32_16x16x32_bf16 v[98:101], v[178:181], v[232:235], v[98:101]
	v_mfma_f32_16x16x32_bf16 v[86:89], v[170:173], v[240:243], v[86:89]
	v_mfma_f32_16x16x32_bf16 v[82:85], v[178:181], v[240:243], v[82:85]
	v_mfma_f32_16x16x32_bf16 v[70:73], v[170:173], v[248:251], v[70:73]
	v_mfma_f32_16x16x32_bf16 v[66:69], v[178:181], v[248:251], v[66:69]
	s_barrier
; #define PG8_STAGE(bufoff, gbase, voff) do { _Pragma("unroll") for (int _i = 0; _i < 2; ++_i) \
;         __builtin_amdgcn_global_load_lds((const unsigned*)((const char*)(gbase) + (voff)[_i]), (PG8_LAS unsigned*)(lds + (bufoff) + ldsw + _i * 8192), 16, 0, 0); } while (0)
; #define PG8_LDA(dst, b, h) do { _Pragma("unroll") for (int m = 0; m < 4; ++m) _Pragma("unroll") for (int k = 0; k < 2; ++k) dst[m][k] = *(const PG8_LAS bf16x8*)(lds + PG8_SA(b, h) + aoff + m * 2048 + k * 1024); } while (0)
; #define PG8_MMA(ai, bj, At, Bt) do { __builtin_amdgcn_s_setprio(1); _Pragma("unroll") for (int m = 0; m < 4; ++m) _Pragma("unroll") for (int n = 0; n < 2; ++n) _Pragma("unroll") for (int k = 0; k < 2; ++k) \
;         acc[ai][bj][m][n] = __builtin_amdgcn_mfma_f32_16x16x32_bf16(Bt[n][k], At[m][k], acc[ai][bj][m][n], 0, 0, 0); __builtin_amdgcn_s_setprio(0); } while (0)
; #define PG8_WAIT_V(n) asm volatile("s_waitcnt vmcnt(" #n ")" ::: "memory")
; #define PG8_WAIT_L(n) asm volatile("s_waitcnt lgkmcnt(" #n ")" ::: "memory")
; #define PG8_BAR __builtin_amdgcn_s_barrier()
; #define PG8_SCHED __builtin_amdgcn_sched_barrier(0)
; template <class Epi, class Sched, bool ALIGN_EPI = false, bool SP2 = false>
; __device__ __forceinline__ void gemm_phase(PG8_LAS unsigned char* lds, const Gemm g, const Sched& S, const Epi& E, int tid_in) {
;     ...
;             PG8_LDA(At, 1, 1); PG8_STAGE(PG8_SB(1, 0), b3, voffB); PG8_STAGE(PG8_SB(1, 1), b3 + hstep, voffB); PG8_STAGE(PG8_SA(1, 0), a3, voffA);
;             PG8_WAIT_V(8); PG8_WAIT_L(0); PG8_BAR; PG8_MMA(1, 0, At, B0); PG8_MMA(1, 1, At, B1); PG8_BAR; PG8_SCHED;
;     ...
;         }
;         if constexpr (ALIGN_EPI) { if (wr == 0) PG8_BAR; }
	s_add_i32 s30, s49, s73
	v_lshl_add_u64 v[144:145], v[144:145], 0, s[54:55]
	s_mov_b32 m0, s30
	ds_read_b128 v[182:185], v152 offset:49152
	ds_read_b128 v[196:199], v152 offset:50176
	ds_read_b128 v[228:231], v152 offset:51200
	ds_read_b128 v[232:235], v152 offset:52224
	ds_read_b128 v[236:239], v152 offset:53248
	ds_read_b128 v[240:243], v152 offset:54272
	ds_read_b128 v[244:247], v152 offset:55296
	ds_read_b128 v[248:251], v152 offset:56320
	global_load_lds_dwordx4 v[144:145], off
	s_add_i32 m0, s30, 0x2000
	s_add_u32 s28, s28, 0x40080
	v_lshl_add_u64 v[144:145], v[148:149], 0, s[54:55]
	s_addc_u32 s29, s29, 0
	s_add_i32 s30, s52, s73
	global_load_lds_dwordx4 v[144:145], off
	v_lshl_add_u64 v[144:145], s[28:29], 0, v[0:1]
	s_mov_b32 m0, s30
	s_nop 0
	global_load_lds_dwordx4 v[144:145], off
	v_lshl_add_u64 v[144:145], s[28:29], 0, v[134:135]
	s_add_i32 m0, s30, 0x2000
	s_nop 0
	global_load_lds_dwordx4 v[144:145], off
	v_lshl_add_u64 v[144:145], v[186:187], 0, s[54:55]
	s_mov_b32 m0, s78
	s_nop 0
	global_load_lds_dwordx4 v[144:145], off
	v_lshl_add_u64 v[144:145], v[218:219], 0, s[54:55]
	s_mov_b32 m0, s79
	s_nop 0
	global_load_lds_dwordx4 v[144:145], off
	s_waitcnt vmcnt(8)
	s_waitcnt lgkmcnt(0)
	s_barrier
	s_waitcnt lgkmcnt(0)
	v_mfma_f32_16x16x32_bf16 v[62:65], v[140:143], v[182:185], v[62:65]
	v_mfma_f32_16x16x32_bf16 v[58:61], v[158:161], v[182:185], v[58:61]
	v_mfma_f32_16x16x32_bf16 v[46:49], v[140:143], v[228:231], v[46:49]
	v_mfma_f32_16x16x32_bf16 v[42:45], v[158:161], v[228:231], v[42:45]
	v_mfma_f32_16x16x32_bf16 v[30:33], v[140:143], v[236:239], v[30:33]
	v_mfma_f32_16x16x32_bf16 v[26:29], v[158:161], v[236:239], v[26:29]
	v_mfma_f32_16x16x32_bf16 v[14:17], v[140:143], v[244:247], v[14:17]
	v_mfma_f32_16x16x32_bf16 v[10:13], v[158:161], v[244:247], v[10:13]
	v_mfma_f32_16x16x32_bf16 v[62:65], v[154:157], v[196:199], v[62:65]
	v_mfma_f32_16x16x32_bf16 v[58:61], v[162:165], v[196:199], v[58:61]
	v_mfma_f32_16x16x32_bf16 v[46:49], v[154:157], v[232:235], v[46:49]
	v_mfma_f32_16x16x32_bf16 v[42:45], v[162:165], v[232:235], v[42:45]
	v_mfma_f32_16x16x32_bf16 v[30:33], v[154:157], v[240:243], v[30:33]
	v_mfma_f32_16x16x32_bf16 v[26:29], v[162:165], v[240:243], v[26:29]
	v_mfma_f32_16x16x32_bf16 v[14:17], v[154:157], v[248:251], v[14:17]
	v_mfma_f32_16x16x32_bf16 v[10:13], v[162:165], v[248:251], v[10:13]
	v_mfma_f32_16x16x32_bf16 v[54:57], v[166:169], v[182:185], v[54:57]
	v_mfma_f32_16x16x32_bf16 v[50:53], v[174:177], v[182:185], v[50:53]
	v_mfma_f32_16x16x32_bf16 v[38:41], v[166:169], v[228:231], v[38:41]
	v_mfma_f32_16x16x32_bf16 v[34:37], v[174:177], v[228:231], v[34:37]
	v_mfma_f32_16x16x32_bf16 v[22:25], v[166:169], v[236:239], v[22:25]
	v_mfma_f32_16x16x32_bf16 v[18:21], v[174:177], v[236:239], v[18:21]
	v_mfma_f32_16x16x32_bf16 v[6:9], v[166:169], v[244:247], v[6:9]
	v_mfma_f32_16x16x32_bf16 v[2:5], v[174:177], v[244:247], v[2:5]
	v_mfma_f32_16x16x32_bf16 v[54:57], v[170:173], v[196:199], v[54:57]
	v_mfma_f32_16x16x32_bf16 v[50:53], v[178:181], v[196:199], v[50:53]
	v_mfma_f32_16x16x32_bf16 v[38:41], v[170:173], v[232:235], v[38:41]
	v_mfma_f32_16x16x32_bf16 v[34:37], v[178:181], v[232:235], v[34:37]
	v_mfma_f32_16x16x32_bf16 v[22:25], v[170:173], v[240:243], v[22:25]
	v_mfma_f32_16x16x32_bf16 v[18:21], v[178:181], v[240:243], v[18:21]
	v_mfma_f32_16x16x32_bf16 v[6:9], v[170:173], v[248:251], v[6:9]
	v_mfma_f32_16x16x32_bf16 v[2:5], v[178:181], v[248:251], v[2:5]
	s_barrier
	s_add_i32 s48, s48, 2
	s_add_u32 s26, s26, 0x100
	s_addc_u32 s27, s27, 0
	s_add_u32 s46, s46, 0x100
	s_addc_u32 s47, s47, 0
	s_cmp_gt_u32 s48, 13
	s_cbranch_scc0 .LBB0_920
	s_setprio 0
	s_and_b64 vcc, exec, s[14:15]
	s_cbranch_vccz .LBB0_923
	s_barrier
